# decode compute loops: one counted lgkmcnt wait per MFMA pair as well (on top of the pair-wait prompt loop)
# speedup vs baseline: 1.0023x; 1.0010x over previous
.LBB0_737:
	v_add_u32_e32 v16, s58, v182
	ds_read_b128 v[4:7], v16 offset:0
	ds_read_b128 v[194:197], v182 offset:0
	ds_read_b128 v[198:201], v182 offset:18944
	ds_read_b128 v[8:11], v16 offset:32
	ds_read_b128 v[202:205], v182 offset:32
	ds_read_b128 v[206:209], v182 offset:18976
	ds_read_b128 v[12:15], v16 offset:64
	ds_read_b128 v[210:213], v182 offset:64
	ds_read_b128 v[214:217], v182 offset:19008
	s_waitcnt lgkmcnt(6)
	v_mfma_f32_32x32x16_bf16 v[162:177], v[194:197], v[4:7], 0
	ds_read_b128 v[186:189], v16 offset:96
	ds_read_b128 v[234:237], v182 offset:96
	ds_read_b128 v[238:241], v182 offset:19040
	ds_read_b128 v[190:193], v16 offset:128
	ds_read_b128 v[242:245], v182 offset:128
	v_mfma_f32_32x32x16_bf16 v[146:161], v[198:201], v[4:7], 0
	ds_read_b128 v[246:249], v182 offset:19072
	s_waitcnt lgkmcnt(9)
	v_mfma_f32_32x32x16_bf16 v[162:177], v[202:205], v[8:11], v[162:177]
	ds_read_b128 v[4:7], v16 offset:160
	ds_read_b128 v[194:197], v182 offset:160
	v_mfma_f32_32x32x16_bf16 v[146:161], v[206:209], v[8:11], v[146:161]
	ds_read_b128 v[198:201], v182 offset:19104
	s_waitcnt lgkmcnt(9)
	v_mfma_f32_32x32x16_bf16 v[162:177], v[210:213], v[12:15], v[162:177]
	ds_read_b128 v[8:11], v16 offset:192
	ds_read_b128 v[202:205], v182 offset:192
	v_mfma_f32_32x32x16_bf16 v[146:161], v[214:217], v[12:15], v[146:161]
	ds_read_b128 v[206:209], v182 offset:19136
	s_waitcnt lgkmcnt(9)
	v_mfma_f32_32x32x16_bf16 v[162:177], v[234:237], v[186:189], v[162:177]
	ds_read_b128 v[12:15], v16 offset:224
	ds_read_b128 v[210:213], v182 offset:224
	v_mfma_f32_32x32x16_bf16 v[146:161], v[238:241], v[186:189], v[146:161]
	ds_read_b128 v[214:217], v182 offset:19168
	s_waitcnt lgkmcnt(9)
	v_mfma_f32_32x32x16_bf16 v[162:177], v[242:245], v[190:193], v[162:177]
	ds_read_b128 v[186:189], v16 offset:256
	ds_read_b128 v[234:237], v182 offset:256
	v_mfma_f32_32x32x16_bf16 v[146:161], v[246:249], v[190:193], v[146:161]
	ds_read_b128 v[238:241], v182 offset:19200
	s_waitcnt lgkmcnt(9)
	v_mfma_f32_32x32x16_bf16 v[162:177], v[194:197], v[4:7], v[162:177]
	ds_read_b128 v[190:193], v16 offset:288
	ds_read_b128 v[242:245], v182 offset:288
	v_mfma_f32_32x32x16_bf16 v[146:161], v[198:201], v[4:7], v[146:161]
	ds_read_b128 v[246:249], v182 offset:19232
	s_waitcnt lgkmcnt(9)
	v_mfma_f32_32x32x16_bf16 v[162:177], v[202:205], v[8:11], v[162:177]
	ds_read_b128 v[4:7], v16 offset:320
	ds_read_b128 v[194:197], v182 offset:320
	v_mfma_f32_32x32x16_bf16 v[146:161], v[206:209], v[8:11], v[146:161]
	ds_read_b128 v[198:201], v182 offset:19264
	s_waitcnt lgkmcnt(9)
	v_mfma_f32_32x32x16_bf16 v[162:177], v[210:213], v[12:15], v[162:177]
	ds_read_b128 v[8:11], v16 offset:352
	ds_read_b128 v[202:205], v182 offset:352
	v_mfma_f32_32x32x16_bf16 v[146:161], v[214:217], v[12:15], v[146:161]
	ds_read_b128 v[206:209], v182 offset:19296
	s_waitcnt lgkmcnt(9)
	v_mfma_f32_32x32x16_bf16 v[162:177], v[234:237], v[186:189], v[162:177]
	ds_read_b128 v[12:15], v16 offset:384
	ds_read_b128 v[210:213], v182 offset:384
	v_mfma_f32_32x32x16_bf16 v[146:161], v[238:241], v[186:189], v[146:161]
	ds_read_b128 v[214:217], v182 offset:19328
	s_waitcnt lgkmcnt(9)
	v_mfma_f32_32x32x16_bf16 v[162:177], v[242:245], v[190:193], v[162:177]
	ds_read_b128 v[186:189], v16 offset:416
	ds_read_b128 v[234:237], v182 offset:416
	v_mfma_f32_32x32x16_bf16 v[146:161], v[246:249], v[190:193], v[146:161]
	ds_read_b128 v[238:241], v182 offset:19360
	s_waitcnt lgkmcnt(9)
	v_mfma_f32_32x32x16_bf16 v[162:177], v[194:197], v[4:7], v[162:177]
	ds_read_b128 v[190:193], v16 offset:448
	ds_read_b128 v[242:245], v182 offset:448
	v_mfma_f32_32x32x16_bf16 v[146:161], v[198:201], v[4:7], v[146:161]
	ds_read_b128 v[246:249], v182 offset:19392
	s_waitcnt lgkmcnt(9)
	v_mfma_f32_32x32x16_bf16 v[162:177], v[202:205], v[8:11], v[162:177]
	ds_read_b128 v[4:7], v16 offset:480
	ds_read_b128 v[194:197], v182 offset:480
	v_mfma_f32_32x32x16_bf16 v[146:161], v[206:209], v[8:11], v[146:161]
	ds_read_b128 v[198:201], v182 offset:19424
	s_waitcnt lgkmcnt(9)
	v_mfma_f32_32x32x16_bf16 v[162:177], v[210:213], v[12:15], v[162:177]
	ds_read_b128 v[8:11], v16 offset:512
	ds_read_b128 v[202:205], v182 offset:512
	v_mfma_f32_32x32x16_bf16 v[146:161], v[214:217], v[12:15], v[146:161]
	ds_read_b128 v[206:209], v182 offset:19456
	s_waitcnt lgkmcnt(9)
	v_mfma_f32_32x32x16_bf16 v[162:177], v[234:237], v[186:189], v[162:177]
	ds_read_b128 v[12:15], v16 offset:544
	ds_read_b128 v[210:213], v182 offset:544
	v_mfma_f32_32x32x16_bf16 v[146:161], v[238:241], v[186:189], v[146:161]
	ds_read_b128 v[214:217], v182 offset:19488
	s_waitcnt lgkmcnt(9)
	v_mfma_f32_32x32x16_bf16 v[162:177], v[242:245], v[190:193], v[162:177]
	v_mfma_f32_32x32x16_bf16 v[146:161], v[246:249], v[190:193], v[146:161]
	s_waitcnt lgkmcnt(6)
	v_mfma_f32_32x32x16_bf16 v[162:177], v[194:197], v[4:7], v[162:177]
	v_mfma_f32_32x32x16_bf16 v[146:161], v[198:201], v[4:7], v[146:161]
	s_waitcnt lgkmcnt(3)
	v_mfma_f32_32x32x16_bf16 v[162:177], v[202:205], v[8:11], v[162:177]
	v_mfma_f32_32x32x16_bf16 v[146:161], v[206:209], v[8:11], v[146:161]
	s_waitcnt lgkmcnt(0)
	v_mfma_f32_32x32x16_bf16 v[162:177], v[210:213], v[12:15], v[162:177]
	v_mfma_f32_32x32x16_bf16 v[146:161], v[214:217], v[12:15], v[146:161]
	ds_read_b64_tr_b16 v[190:191], v184 offset:0
	ds_read_b64_tr_b16 v[192:193], v184 offset:4736
	ds_read_b64_tr_b16 v[194:195], v184 offset:64
	ds_read_b64_tr_b16 v[196:197], v184 offset:4800
	ds_read_b64_tr_b16 v[198:199], v184 offset:128
	ds_read_b64_tr_b16 v[200:201], v184 offset:4864
	ds_read_b64_tr_b16 v[202:203], v184 offset:192
	ds_read_b64_tr_b16 v[204:205], v184 offset:4928
	ds_read_b64_tr_b16 v[206:207], v184 offset:256
	ds_read_b64_tr_b16 v[208:209], v184 offset:4992
	ds_read_b64_tr_b16 v[210:211], v184 offset:320
	ds_read_b64_tr_b16 v[212:213], v184 offset:5056
	ds_read_b64_tr_b16 v[214:215], v184 offset:384
	ds_read_b64_tr_b16 v[216:217], v184 offset:5120
	v_max3_f32 v2, v162, v146, v163
	v_max3_f32 v17, v147, v164, v148
	v_max3_f32 v2, v2, v165, v149
	v_max3_f32 v17, v17, v166, v150
	v_max3_f32 v2, v2, v167, v151
	v_max3_f32 v17, v17, v168, v152
	v_max3_f32 v2, v2, v169, v153
	v_max3_f32 v17, v17, v170, v154
	v_max3_f32 v2, v2, v171, v155
	v_max3_f32 v17, v17, v172, v156
	v_max3_f32 v2, v2, v173, v157
	v_max3_f32 v17, v17, v174, v158
	v_max3_f32 v2, v2, v175, v159
	v_max3_f32 v17, v17, v176, v160
	v_max3_f32 v2, v2, v17, v177
	v_max_f32_e32 v2, v2, v161
	v_mov_b32_e32 v218, v2
	v_add_f32_e32 v233, 0x41000000, v178
	v_mov_b32_e32 v254, 0
	v_permlane32_swap_b32_e32 v2, v218
	v_max_f32_e32 v2, v2, v218
	v_mul_f32_e32 v2, 0x3e16c740, v2
	v_cmp_gt_f32_e32 vcc, v2, v233
	s_cbranch_vccz .Ldc0_nr0
	v_max_f32_e32 v2, v178, v2
	v_sub_f32_e32 v219, v178, v2
	v_exp_f32_e32 v219, v219
	v_mov_b32_e32 v178, v2
	v_mov_b32_e32 v218, v2
	v_mul_f32_e32 v183, v183, v219
	v_mul_f32_e32 v130, v130, v219
	v_mul_f32_e32 v131, v131, v219
	v_mul_f32_e32 v132, v132, v219
	v_mul_f32_e32 v133, v133, v219
	v_mul_f32_e32 v134, v134, v219
	v_mul_f32_e32 v135, v135, v219
	v_mul_f32_e32 v136, v136, v219
	v_mul_f32_e32 v137, v137, v219
	v_mul_f32_e32 v138, v138, v219
	v_mul_f32_e32 v139, v139, v219
	v_mul_f32_e32 v140, v140, v219
	v_mul_f32_e32 v141, v141, v219
	v_mul_f32_e32 v142, v142, v219
	v_mul_f32_e32 v143, v143, v219
	v_mul_f32_e32 v144, v144, v219
	v_mul_f32_e32 v145, v145, v219
	v_mul_f32_e32 v114, v114, v219
	v_mul_f32_e32 v115, v115, v219
	v_mul_f32_e32 v116, v116, v219
	v_mul_f32_e32 v117, v117, v219
	v_mul_f32_e32 v118, v118, v219
	v_mul_f32_e32 v119, v119, v219
	v_mul_f32_e32 v120, v120, v219
	v_mul_f32_e32 v121, v121, v219
	v_mul_f32_e32 v122, v122, v219
	v_mul_f32_e32 v123, v123, v219
	v_mul_f32_e32 v124, v124, v219
	v_mul_f32_e32 v125, v125, v219
	v_mul_f32_e32 v126, v126, v219
	v_mul_f32_e32 v127, v127, v219
	v_mul_f32_e32 v128, v128, v219
	v_mul_f32_e32 v129, v129, v219
	v_mul_f32_e32 v98, v98, v219
	v_mul_f32_e32 v99, v99, v219
	v_mul_f32_e32 v100, v100, v219
	v_mul_f32_e32 v101, v101, v219
	v_mul_f32_e32 v102, v102, v219
	v_mul_f32_e32 v103, v103, v219
	v_mul_f32_e32 v104, v104, v219
	v_mul_f32_e32 v105, v105, v219
	v_mul_f32_e32 v106, v106, v219
	v_mul_f32_e32 v107, v107, v219
	v_mul_f32_e32 v108, v108, v219
	v_mul_f32_e32 v109, v109, v219
	v_mul_f32_e32 v110, v110, v219
	v_mul_f32_e32 v111, v111, v219
	v_mul_f32_e32 v112, v112, v219
	v_mul_f32_e32 v113, v113, v219
	v_mul_f32_e32 v82, v82, v219
	v_mul_f32_e32 v83, v83, v219
	v_mul_f32_e32 v84, v84, v219
	v_mul_f32_e32 v85, v85, v219
	v_mul_f32_e32 v86, v86, v219
	v_mul_f32_e32 v87, v87, v219
	v_mul_f32_e32 v88, v88, v219
	v_mul_f32_e32 v89, v89, v219
	v_mul_f32_e32 v90, v90, v219
	v_mul_f32_e32 v91, v91, v219
	v_mul_f32_e32 v92, v92, v219
	v_mul_f32_e32 v93, v93, v219
	v_mul_f32_e32 v94, v94, v219
	v_mul_f32_e32 v95, v95, v219
	v_mul_f32_e32 v96, v96, v219
	v_mul_f32_e32 v97, v97, v219
	v_mul_f32_e32 v66, v66, v219
	v_mul_f32_e32 v67, v67, v219
	v_mul_f32_e32 v68, v68, v219
	v_mul_f32_e32 v69, v69, v219
	v_mul_f32_e32 v70, v70, v219
	v_mul_f32_e32 v71, v71, v219
	v_mul_f32_e32 v72, v72, v219
	v_mul_f32_e32 v73, v73, v219
	v_mul_f32_e32 v74, v74, v219
	v_mul_f32_e32 v75, v75, v219
	v_mul_f32_e32 v76, v76, v219
	v_mul_f32_e32 v77, v77, v219
	v_mul_f32_e32 v78, v78, v219
	v_mul_f32_e32 v79, v79, v219
	v_mul_f32_e32 v80, v80, v219
	v_mul_f32_e32 v81, v81, v219
	v_mul_f32_e32 v50, v50, v219
	v_mul_f32_e32 v51, v51, v219
	v_mul_f32_e32 v52, v52, v219
	v_mul_f32_e32 v53, v53, v219
	v_mul_f32_e32 v54, v54, v219
	v_mul_f32_e32 v55, v55, v219
	v_mul_f32_e32 v56, v56, v219
	v_mul_f32_e32 v57, v57, v219
	v_mul_f32_e32 v58, v58, v219
	v_mul_f32_e32 v59, v59, v219
	v_mul_f32_e32 v60, v60, v219
	v_mul_f32_e32 v61, v61, v219
	v_mul_f32_e32 v62, v62, v219
	v_mul_f32_e32 v63, v63, v219
	v_mul_f32_e32 v64, v64, v219
	v_mul_f32_e32 v65, v65, v219
	v_mul_f32_e32 v34, v34, v219
	v_mul_f32_e32 v35, v35, v219
	v_mul_f32_e32 v36, v36, v219
	v_mul_f32_e32 v37, v37, v219
	v_mul_f32_e32 v38, v38, v219
	v_mul_f32_e32 v39, v39, v219
	v_mul_f32_e32 v40, v40, v219
	v_mul_f32_e32 v41, v41, v219
	v_mul_f32_e32 v42, v42, v219
	v_mul_f32_e32 v43, v43, v219
	v_mul_f32_e32 v44, v44, v219
	v_mul_f32_e32 v45, v45, v219
	v_mul_f32_e32 v46, v46, v219
	v_mul_f32_e32 v47, v47, v219
	v_mul_f32_e32 v48, v48, v219
	v_mul_f32_e32 v49, v49, v219
	v_mul_f32_e32 v18, v18, v219
	v_mul_f32_e32 v19, v19, v219
	v_mul_f32_e32 v20, v20, v219
	v_mul_f32_e32 v21, v21, v219
	v_mul_f32_e32 v22, v22, v219
	v_mul_f32_e32 v23, v23, v219
	v_mul_f32_e32 v24, v24, v219
	v_mul_f32_e32 v25, v25, v219
	v_mul_f32_e32 v26, v26, v219
	v_mul_f32_e32 v27, v27, v219
	v_mul_f32_e32 v28, v28, v219
	v_mul_f32_e32 v29, v29, v219
	v_mul_f32_e32 v30, v30, v219
	v_mul_f32_e32 v31, v31, v219
	v_mul_f32_e32 v32, v32, v219
	v_mul_f32_e32 v33, v33, v219
.Ldc0_nr0:
	v_fma_f32 v162, v162, s51, -v178
	v_fma_f32 v146, v146, s51, -v178
	v_fma_f32 v163, v163, s51, -v178
	v_exp_f32_e32 v162, v162
	v_fma_f32 v147, v147, s51, -v178
	v_exp_f32_e32 v146, v146
	v_fma_f32 v164, v164, s51, -v178
	v_exp_f32_e32 v163, v163
	v_fma_f32 v148, v148, s51, -v178
	v_exp_f32_e32 v147, v147
	v_fma_f32 v165, v165, s51, -v178
	v_add_f32_e32 v218, v162, v146
	v_exp_f32_e32 v164, v164
	v_fma_f32 v149, v149, s51, -v178
	v_exp_f32_e32 v148, v148
	v_cvt_pk_bf16_f32 v4, v162, v163
	v_fma_f32 v166, v166, s51, -v178
	v_add_f32_e32 v233, v163, v147
	v_exp_f32_e32 v165, v165
	v_add_f32_e32 v254, v254, v218
	v_cvt_pk_bf16_f32 v12, v146, v147
	v_fma_f32 v150, v150, s51, -v178
	v_exp_f32_e32 v149, v149
	v_fma_f32 v167, v167, s51, -v178
	v_add_f32_e32 v17, v164, v148
	v_exp_f32_e32 v166, v166
	v_add_f32_e32 v254, v254, v233
	v_fma_f32 v151, v151, s51, -v178
	v_exp_f32_e32 v150, v150
	v_cvt_pk_bf16_f32 v5, v164, v165
	v_fma_f32 v168, v168, s51, -v178
	v_add_f32_e32 v219, v165, v149
	v_exp_f32_e32 v167, v167
	v_add_f32_e32 v254, v254, v17
	v_cvt_pk_bf16_f32 v13, v148, v149
	v_fma_f32 v152, v152, s51, -v178
	v_exp_f32_e32 v151, v151
	v_fma_f32 v169, v169, s51, -v178
	v_add_f32_e32 v218, v166, v150
	v_exp_f32_e32 v168, v168
	v_add_f32_e32 v254, v254, v219
	v_fma_f32 v153, v153, s51, -v178
	v_exp_f32_e32 v152, v152
	v_cvt_pk_bf16_f32 v6, v166, v167
	v_fma_f32 v170, v170, s51, -v178
	v_add_f32_e32 v233, v167, v151
	v_exp_f32_e32 v169, v169
	v_add_f32_e32 v254, v254, v218
	v_cvt_pk_bf16_f32 v14, v150, v151
	v_fma_f32 v154, v154, s51, -v178
	v_exp_f32_e32 v153, v153
	v_fma_f32 v171, v171, s51, -v178
	v_add_f32_e32 v17, v168, v152
	v_exp_f32_e32 v170, v170
	v_add_f32_e32 v254, v254, v233
	v_fma_f32 v155, v155, s51, -v178
	v_exp_f32_e32 v154, v154
	v_cvt_pk_bf16_f32 v7, v168, v169
	v_fma_f32 v172, v172, s51, -v178
	v_add_f32_e32 v219, v169, v153
	v_exp_f32_e32 v171, v171
	v_add_f32_e32 v254, v254, v17
	v_cvt_pk_bf16_f32 v15, v152, v153
	v_fma_f32 v156, v156, s51, -v178
	v_exp_f32_e32 v155, v155
	v_fma_f32 v173, v173, s51, -v178
	v_add_f32_e32 v218, v170, v154
	v_exp_f32_e32 v172, v172
	v_add_f32_e32 v254, v254, v219
	v_fma_f32 v157, v157, s51, -v178
	v_exp_f32_e32 v156, v156
	v_cvt_pk_bf16_f32 v8, v170, v171
	v_fma_f32 v174, v174, s51, -v178
	v_add_f32_e32 v233, v171, v155
	v_exp_f32_e32 v173, v173
	v_add_f32_e32 v254, v254, v218
	v_cvt_pk_bf16_f32 v186, v154, v155
	v_fma_f32 v158, v158, s51, -v178
	v_exp_f32_e32 v157, v157
	v_fma_f32 v175, v175, s51, -v178
	v_add_f32_e32 v17, v172, v156
	v_exp_f32_e32 v174, v174
	v_add_f32_e32 v254, v254, v233
	v_fma_f32 v159, v159, s51, -v178
	v_exp_f32_e32 v158, v158
	v_cvt_pk_bf16_f32 v9, v172, v173
	v_fma_f32 v176, v176, s51, -v178
	v_add_f32_e32 v219, v173, v157
	v_exp_f32_e32 v175, v175
	v_add_f32_e32 v254, v254, v17
	v_cvt_pk_bf16_f32 v187, v156, v157
	v_fma_f32 v160, v160, s51, -v178
	v_exp_f32_e32 v159, v159
	v_fma_f32 v177, v177, s51, -v178
	v_add_f32_e32 v218, v174, v158
	v_exp_f32_e32 v176, v176
	v_add_f32_e32 v254, v254, v219
	v_fma_f32 v161, v161, s51, -v178
	v_exp_f32_e32 v160, v160
	v_cvt_pk_bf16_f32 v10, v174, v175
	v_add_f32_e32 v233, v175, v159
	v_exp_f32_e32 v177, v177
	v_add_f32_e32 v254, v254, v218
	v_cvt_pk_bf16_f32 v188, v158, v159
	v_exp_f32_e32 v161, v161
	v_add_f32_e32 v17, v176, v160
	v_add_f32_e32 v254, v254, v233
	v_cvt_pk_bf16_f32 v11, v176, v177
	v_add_f32_e32 v219, v177, v161
	v_add_f32_e32 v254, v254, v17
	v_cvt_pk_bf16_f32 v189, v160, v161
	v_add_f32_e32 v254, v254, v219
	v_add_f32_e32 v183, v183, v254
	s_waitcnt lgkmcnt(12)
	v_mfma_f32_32x32x16_bf16 v[130:145], v[190:193], v[4:7], v[130:145]
	ds_read_b64_tr_b16 v[234:235], v184 offset:448
	ds_read_b64_tr_b16 v[236:237], v184 offset:5184
	s_waitcnt lgkmcnt(12)
	v_mfma_f32_32x32x16_bf16 v[114:129], v[194:197], v[4:7], v[114:129]
	ds_read_b64_tr_b16 v[238:239], v184 offset:9472
	ds_read_b64_tr_b16 v[240:241], v184 offset:14208
	s_waitcnt lgkmcnt(12)
	v_mfma_f32_32x32x16_bf16 v[98:113], v[198:201], v[4:7], v[98:113]
	ds_read_b64_tr_b16 v[242:243], v184 offset:9536
	ds_read_b64_tr_b16 v[244:245], v184 offset:14272
	s_waitcnt lgkmcnt(12)
	v_mfma_f32_32x32x16_bf16 v[82:97], v[202:205], v[4:7], v[82:97]
	ds_read_b64_tr_b16 v[246:247], v184 offset:9600
	ds_read_b64_tr_b16 v[248:249], v184 offset:14336
	s_waitcnt lgkmcnt(12)
	v_mfma_f32_32x32x16_bf16 v[66:81], v[206:209], v[4:7], v[66:81]
	ds_read_b64_tr_b16 v[250:251], v184 offset:9664
	ds_read_b64_tr_b16 v[252:253], v184 offset:14400
	s_waitcnt lgkmcnt(12)
	v_mfma_f32_32x32x16_bf16 v[50:65], v[210:213], v[4:7], v[50:65]
	ds_read_b64_tr_b16 v[190:191], v184 offset:9728
	ds_read_b64_tr_b16 v[192:193], v184 offset:14464
	s_waitcnt lgkmcnt(12)
	v_mfma_f32_32x32x16_bf16 v[34:49], v[214:217], v[4:7], v[34:49]
	ds_read_b64_tr_b16 v[194:195], v184 offset:9792
	ds_read_b64_tr_b16 v[196:197], v184 offset:14528
	s_waitcnt lgkmcnt(12)
	v_mfma_f32_32x32x16_bf16 v[18:33], v[234:237], v[4:7], v[18:33]
	ds_read_b64_tr_b16 v[198:199], v184 offset:9856
	ds_read_b64_tr_b16 v[200:201], v184 offset:14592
	s_waitcnt lgkmcnt(12)
	v_mfma_f32_32x32x16_bf16 v[130:145], v[238:241], v[8:11], v[130:145]
	ds_read_b64_tr_b16 v[202:203], v184 offset:9920
	ds_read_b64_tr_b16 v[204:205], v184 offset:14656
	s_waitcnt lgkmcnt(12)
	v_mfma_f32_32x32x16_bf16 v[114:129], v[242:245], v[8:11], v[114:129]
	ds_read_b64_tr_b16 v[206:207], v184 offset:18944
	ds_read_b64_tr_b16 v[208:209], v184 offset:23680
	s_waitcnt lgkmcnt(12)
	v_mfma_f32_32x32x16_bf16 v[98:113], v[246:249], v[8:11], v[98:113]
	ds_read_b64_tr_b16 v[210:211], v184 offset:19008
	ds_read_b64_tr_b16 v[212:213], v184 offset:23744
	s_waitcnt lgkmcnt(12)
	v_mfma_f32_32x32x16_bf16 v[82:97], v[250:253], v[8:11], v[82:97]
	ds_read_b64_tr_b16 v[214:215], v184 offset:19072
	ds_read_b64_tr_b16 v[216:217], v184 offset:23808
	s_waitcnt lgkmcnt(12)
	v_mfma_f32_32x32x16_bf16 v[66:81], v[190:193], v[8:11], v[66:81]
	ds_read_b64_tr_b16 v[234:235], v184 offset:19136
	ds_read_b64_tr_b16 v[236:237], v184 offset:23872
	s_waitcnt lgkmcnt(12)
	v_mfma_f32_32x32x16_bf16 v[50:65], v[194:197], v[8:11], v[50:65]
	ds_read_b64_tr_b16 v[238:239], v184 offset:19200
	ds_read_b64_tr_b16 v[240:241], v184 offset:23936
	s_waitcnt lgkmcnt(12)
	v_mfma_f32_32x32x16_bf16 v[34:49], v[198:201], v[8:11], v[34:49]
	ds_read_b64_tr_b16 v[242:243], v184 offset:19264
	ds_read_b64_tr_b16 v[244:245], v184 offset:24000
	s_waitcnt lgkmcnt(12)
	v_mfma_f32_32x32x16_bf16 v[18:33], v[202:205], v[8:11], v[18:33]
	ds_read_b64_tr_b16 v[246:247], v184 offset:19328
	ds_read_b64_tr_b16 v[248:249], v184 offset:24064
	s_waitcnt lgkmcnt(12)
	v_mfma_f32_32x32x16_bf16 v[130:145], v[206:209], v[12:15], v[130:145]
	ds_read_b64_tr_b16 v[250:251], v184 offset:19392
	ds_read_b64_tr_b16 v[252:253], v184 offset:24128
	s_waitcnt lgkmcnt(12)
	v_mfma_f32_32x32x16_bf16 v[114:129], v[210:213], v[12:15], v[114:129]
	ds_read_b64_tr_b16 v[190:191], v184 offset:28416
	ds_read_b64_tr_b16 v[192:193], v184 offset:33152
	s_waitcnt lgkmcnt(12)
	v_mfma_f32_32x32x16_bf16 v[98:113], v[214:217], v[12:15], v[98:113]
	ds_read_b64_tr_b16 v[194:195], v184 offset:28480
	ds_read_b64_tr_b16 v[196:197], v184 offset:33216
	s_waitcnt lgkmcnt(12)
	v_mfma_f32_32x32x16_bf16 v[82:97], v[234:237], v[12:15], v[82:97]
	ds_read_b64_tr_b16 v[198:199], v184 offset:28544
	ds_read_b64_tr_b16 v[200:201], v184 offset:33280
	s_waitcnt lgkmcnt(12)
	v_mfma_f32_32x32x16_bf16 v[66:81], v[238:241], v[12:15], v[66:81]
	ds_read_b64_tr_b16 v[202:203], v184 offset:28608
	ds_read_b64_tr_b16 v[204:205], v184 offset:33344
	s_waitcnt lgkmcnt(12)
	v_mfma_f32_32x32x16_bf16 v[50:65], v[242:245], v[12:15], v[50:65]
	ds_read_b64_tr_b16 v[206:207], v184 offset:28672
	ds_read_b64_tr_b16 v[208:209], v184 offset:33408
	s_waitcnt lgkmcnt(12)
	v_mfma_f32_32x32x16_bf16 v[34:49], v[246:249], v[12:15], v[34:49]
	ds_read_b64_tr_b16 v[210:211], v184 offset:28736
	ds_read_b64_tr_b16 v[212:213], v184 offset:33472
	s_waitcnt lgkmcnt(12)
	v_mfma_f32_32x32x16_bf16 v[18:33], v[250:253], v[12:15], v[18:33]
	ds_read_b64_tr_b16 v[214:215], v184 offset:28800
	ds_read_b64_tr_b16 v[216:217], v184 offset:33536
	s_waitcnt lgkmcnt(12)
	v_mfma_f32_32x32x16_bf16 v[130:145], v[190:193], v[186:189], v[130:145]
	ds_read_b64_tr_b16 v[234:235], v184 offset:28864
	ds_read_b64_tr_b16 v[236:237], v184 offset:33600
	s_waitcnt lgkmcnt(12)
	v_mfma_f32_32x32x16_bf16 v[114:129], v[194:197], v[186:189], v[114:129]
	s_waitcnt lgkmcnt(10)
	v_mfma_f32_32x32x16_bf16 v[98:113], v[198:201], v[186:189], v[98:113]
	s_waitcnt lgkmcnt(8)
	v_mfma_f32_32x32x16_bf16 v[82:97], v[202:205], v[186:189], v[82:97]
	s_waitcnt lgkmcnt(6)
	v_mfma_f32_32x32x16_bf16 v[66:81], v[206:209], v[186:189], v[66:81]
	s_waitcnt lgkmcnt(4)
	v_mfma_f32_32x32x16_bf16 v[50:65], v[210:213], v[186:189], v[50:65]
	s_waitcnt lgkmcnt(2)
	v_mfma_f32_32x32x16_bf16 v[34:49], v[214:217], v[186:189], v[34:49]
	s_waitcnt lgkmcnt(0)
	v_mfma_f32_32x32x16_bf16 v[18:33], v[234:237], v[186:189], v[18:33]
	s_waitcnt lgkmcnt(0)
	s_barrier
	ds_read_b128 v[4:7], v16 offset:0
	ds_read_b128 v[194:197], v182 offset:37888
	ds_read_b128 v[198:201], v182 offset:56832
	ds_read_b128 v[8:11], v16 offset:32
	ds_read_b128 v[202:205], v182 offset:37920
	ds_read_b128 v[206:209], v182 offset:56864
	ds_read_b128 v[12:15], v16 offset:64
	ds_read_b128 v[210:213], v182 offset:37952
	ds_read_b128 v[214:217], v182 offset:56896
	s_waitcnt lgkmcnt(6)
	v_mfma_f32_32x32x16_bf16 v[162:177], v[194:197], v[4:7], 0
	ds_read_b128 v[186:189], v16 offset:96
	ds_read_b128 v[234:237], v182 offset:37984
	ds_read_b128 v[238:241], v182 offset:56928
	ds_read_b128 v[190:193], v16 offset:128
	ds_read_b128 v[242:245], v182 offset:38016
	v_mfma_f32_32x32x16_bf16 v[146:161], v[198:201], v[4:7], 0
	ds_read_b128 v[246:249], v182 offset:56960
	s_waitcnt lgkmcnt(9)
	v_mfma_f32_32x32x16_bf16 v[162:177], v[202:205], v[8:11], v[162:177]
	ds_read_b128 v[4:7], v16 offset:160
	ds_read_b128 v[194:197], v182 offset:38048
	v_mfma_f32_32x32x16_bf16 v[146:161], v[206:209], v[8:11], v[146:161]
	ds_read_b128 v[198:201], v182 offset:56992
	s_waitcnt lgkmcnt(9)
	v_mfma_f32_32x32x16_bf16 v[162:177], v[210:213], v[12:15], v[162:177]
	ds_read_b128 v[8:11], v16 offset:192
	ds_read_b128 v[202:205], v182 offset:38080
	v_mfma_f32_32x32x16_bf16 v[146:161], v[214:217], v[12:15], v[146:161]
	ds_read_b128 v[206:209], v182 offset:57024
	s_waitcnt lgkmcnt(9)
	v_mfma_f32_32x32x16_bf16 v[162:177], v[234:237], v[186:189], v[162:177]
	ds_read_b128 v[12:15], v16 offset:224
	ds_read_b128 v[210:213], v182 offset:38112
	v_mfma_f32_32x32x16_bf16 v[146:161], v[238:241], v[186:189], v[146:161]
	ds_read_b128 v[214:217], v182 offset:57056
	s_waitcnt lgkmcnt(9)
	v_mfma_f32_32x32x16_bf16 v[162:177], v[242:245], v[190:193], v[162:177]
	ds_read_b128 v[186:189], v16 offset:256
	ds_read_b128 v[234:237], v182 offset:38144
	v_mfma_f32_32x32x16_bf16 v[146:161], v[246:249], v[190:193], v[146:161]
	ds_read_b128 v[238:241], v182 offset:57088
	s_waitcnt lgkmcnt(9)
	v_mfma_f32_32x32x16_bf16 v[162:177], v[194:197], v[4:7], v[162:177]
	ds_read_b128 v[190:193], v16 offset:288
	ds_read_b128 v[242:245], v182 offset:38176
	v_mfma_f32_32x32x16_bf16 v[146:161], v[198:201], v[4:7], v[146:161]
	ds_read_b128 v[246:249], v182 offset:57120
	s_waitcnt lgkmcnt(9)
	v_mfma_f32_32x32x16_bf16 v[162:177], v[202:205], v[8:11], v[162:177]
	ds_read_b128 v[4:7], v16 offset:320
	ds_read_b128 v[194:197], v182 offset:38208
	v_mfma_f32_32x32x16_bf16 v[146:161], v[206:209], v[8:11], v[146:161]
	ds_read_b128 v[198:201], v182 offset:57152
	s_waitcnt lgkmcnt(9)
	v_mfma_f32_32x32x16_bf16 v[162:177], v[210:213], v[12:15], v[162:177]
	ds_read_b128 v[8:11], v16 offset:352
	ds_read_b128 v[202:205], v182 offset:38240
	v_mfma_f32_32x32x16_bf16 v[146:161], v[214:217], v[12:15], v[146:161]
	ds_read_b128 v[206:209], v182 offset:57184
	s_waitcnt lgkmcnt(9)
	v_mfma_f32_32x32x16_bf16 v[162:177], v[234:237], v[186:189], v[162:177]
	ds_read_b128 v[12:15], v16 offset:384
	ds_read_b128 v[210:213], v182 offset:38272
	v_mfma_f32_32x32x16_bf16 v[146:161], v[238:241], v[186:189], v[146:161]
	ds_read_b128 v[214:217], v182 offset:57216
	s_waitcnt lgkmcnt(9)
	v_mfma_f32_32x32x16_bf16 v[162:177], v[242:245], v[190:193], v[162:177]
	ds_read_b128 v[186:189], v16 offset:416
	ds_read_b128 v[234:237], v182 offset:38304
	v_mfma_f32_32x32x16_bf16 v[146:161], v[246:249], v[190:193], v[146:161]
	ds_read_b128 v[238:241], v182 offset:57248
	s_waitcnt lgkmcnt(9)
	v_mfma_f32_32x32x16_bf16 v[162:177], v[194:197], v[4:7], v[162:177]
	ds_read_b128 v[190:193], v16 offset:448
	ds_read_b128 v[242:245], v182 offset:38336
	v_mfma_f32_32x32x16_bf16 v[146:161], v[198:201], v[4:7], v[146:161]
	ds_read_b128 v[246:249], v182 offset:57280
	s_waitcnt lgkmcnt(9)
	v_mfma_f32_32x32x16_bf16 v[162:177], v[202:205], v[8:11], v[162:177]
	ds_read_b128 v[4:7], v16 offset:480
	ds_read_b128 v[194:197], v182 offset:38368
	v_mfma_f32_32x32x16_bf16 v[146:161], v[206:209], v[8:11], v[146:161]
	ds_read_b128 v[198:201], v182 offset:57312
	s_waitcnt lgkmcnt(9)
	v_mfma_f32_32x32x16_bf16 v[162:177], v[210:213], v[12:15], v[162:177]
	ds_read_b128 v[8:11], v16 offset:512
	ds_read_b128 v[202:205], v182 offset:38400
	v_mfma_f32_32x32x16_bf16 v[146:161], v[214:217], v[12:15], v[146:161]
	ds_read_b128 v[206:209], v182 offset:57344
	s_waitcnt lgkmcnt(9)
	v_mfma_f32_32x32x16_bf16 v[162:177], v[234:237], v[186:189], v[162:177]
	ds_read_b128 v[12:15], v16 offset:544
	ds_read_b128 v[210:213], v182 offset:38432
	v_mfma_f32_32x32x16_bf16 v[146:161], v[238:241], v[186:189], v[146:161]
	ds_read_b128 v[214:217], v182 offset:57376
	s_waitcnt lgkmcnt(9)
	v_mfma_f32_32x32x16_bf16 v[162:177], v[242:245], v[190:193], v[162:177]
	v_mfma_f32_32x32x16_bf16 v[146:161], v[246:249], v[190:193], v[146:161]
	s_waitcnt lgkmcnt(6)
	v_mfma_f32_32x32x16_bf16 v[162:177], v[194:197], v[4:7], v[162:177]
	v_mfma_f32_32x32x16_bf16 v[146:161], v[198:201], v[4:7], v[146:161]
	s_waitcnt lgkmcnt(3)
	v_mfma_f32_32x32x16_bf16 v[162:177], v[202:205], v[8:11], v[162:177]
	v_mfma_f32_32x32x16_bf16 v[146:161], v[206:209], v[8:11], v[146:161]
	s_waitcnt lgkmcnt(0)
	v_mfma_f32_32x32x16_bf16 v[162:177], v[210:213], v[12:15], v[162:177]
	v_mfma_f32_32x32x16_bf16 v[146:161], v[214:217], v[12:15], v[146:161]
	ds_read_b64_tr_b16 v[190:191], v185 offset:0
	ds_read_b64_tr_b16 v[192:193], v185 offset:4736
	ds_read_b64_tr_b16 v[194:195], v185 offset:64
	ds_read_b64_tr_b16 v[196:197], v185 offset:4800
	ds_read_b64_tr_b16 v[198:199], v185 offset:128
	ds_read_b64_tr_b16 v[200:201], v185 offset:4864
	ds_read_b64_tr_b16 v[202:203], v185 offset:192
	ds_read_b64_tr_b16 v[204:205], v185 offset:4928
	ds_read_b64_tr_b16 v[206:207], v185 offset:256
	ds_read_b64_tr_b16 v[208:209], v185 offset:4992
	ds_read_b64_tr_b16 v[210:211], v185 offset:320
	ds_read_b64_tr_b16 v[212:213], v185 offset:5056
	ds_read_b64_tr_b16 v[214:215], v185 offset:384
	ds_read_b64_tr_b16 v[216:217], v185 offset:5120
	v_max3_f32 v2, v162, v146, v163
	v_max3_f32 v17, v147, v164, v148
	v_max3_f32 v2, v2, v165, v149
	v_max3_f32 v17, v17, v166, v150
	v_max3_f32 v2, v2, v167, v151
	v_max3_f32 v17, v17, v168, v152
	v_max3_f32 v2, v2, v169, v153
	v_max3_f32 v17, v17, v170, v154
	v_max3_f32 v2, v2, v171, v155
	v_max3_f32 v17, v17, v172, v156
	v_max3_f32 v2, v2, v173, v157
	v_max3_f32 v17, v17, v174, v158
	v_max3_f32 v2, v2, v175, v159
	v_max3_f32 v17, v17, v176, v160
	v_max3_f32 v2, v2, v17, v177
	v_max_f32_e32 v2, v2, v161
	v_mov_b32_e32 v218, v2
	v_add_f32_e32 v233, 0x41000000, v178
	v_mov_b32_e32 v254, 0
	v_permlane32_swap_b32_e32 v2, v218
	v_max_f32_e32 v2, v2, v218
	v_mul_f32_e32 v2, 0x3e16c740, v2
	v_cmp_gt_f32_e32 vcc, v2, v233
	s_cbranch_vccz .Ldc0_nr1
	v_max_f32_e32 v2, v178, v2
	v_sub_f32_e32 v219, v178, v2
	v_exp_f32_e32 v219, v219
	v_mov_b32_e32 v178, v2
	v_mov_b32_e32 v218, v2
	v_mul_f32_e32 v183, v183, v219
	v_mul_f32_e32 v130, v130, v219
	v_mul_f32_e32 v131, v131, v219
	v_mul_f32_e32 v132, v132, v219
	v_mul_f32_e32 v133, v133, v219
	v_mul_f32_e32 v134, v134, v219
	v_mul_f32_e32 v135, v135, v219
	v_mul_f32_e32 v136, v136, v219
	v_mul_f32_e32 v137, v137, v219
	v_mul_f32_e32 v138, v138, v219
	v_mul_f32_e32 v139, v139, v219
	v_mul_f32_e32 v140, v140, v219
	v_mul_f32_e32 v141, v141, v219
	v_mul_f32_e32 v142, v142, v219
	v_mul_f32_e32 v143, v143, v219
	v_mul_f32_e32 v144, v144, v219
	v_mul_f32_e32 v145, v145, v219
	v_mul_f32_e32 v114, v114, v219
	v_mul_f32_e32 v115, v115, v219
	v_mul_f32_e32 v116, v116, v219
	v_mul_f32_e32 v117, v117, v219
	v_mul_f32_e32 v118, v118, v219
	v_mul_f32_e32 v119, v119, v219
	v_mul_f32_e32 v120, v120, v219
	v_mul_f32_e32 v121, v121, v219
	v_mul_f32_e32 v122, v122, v219
	v_mul_f32_e32 v123, v123, v219
	v_mul_f32_e32 v124, v124, v219
	v_mul_f32_e32 v125, v125, v219
	v_mul_f32_e32 v126, v126, v219
	v_mul_f32_e32 v127, v127, v219
	v_mul_f32_e32 v128, v128, v219
	v_mul_f32_e32 v129, v129, v219
	v_mul_f32_e32 v98, v98, v219
	v_mul_f32_e32 v99, v99, v219
	v_mul_f32_e32 v100, v100, v219
	v_mul_f32_e32 v101, v101, v219
	v_mul_f32_e32 v102, v102, v219
	v_mul_f32_e32 v103, v103, v219
	v_mul_f32_e32 v104, v104, v219
	v_mul_f32_e32 v105, v105, v219
	v_mul_f32_e32 v106, v106, v219
	v_mul_f32_e32 v107, v107, v219
	v_mul_f32_e32 v108, v108, v219
	v_mul_f32_e32 v109, v109, v219
	v_mul_f32_e32 v110, v110, v219
	v_mul_f32_e32 v111, v111, v219
	v_mul_f32_e32 v112, v112, v219
	v_mul_f32_e32 v113, v113, v219
	v_mul_f32_e32 v82, v82, v219
	v_mul_f32_e32 v83, v83, v219
	v_mul_f32_e32 v84, v84, v219
	v_mul_f32_e32 v85, v85, v219
	v_mul_f32_e32 v86, v86, v219
	v_mul_f32_e32 v87, v87, v219
	v_mul_f32_e32 v88, v88, v219
	v_mul_f32_e32 v89, v89, v219
	v_mul_f32_e32 v90, v90, v219
	v_mul_f32_e32 v91, v91, v219
	v_mul_f32_e32 v92, v92, v219
	v_mul_f32_e32 v93, v93, v219
	v_mul_f32_e32 v94, v94, v219
	v_mul_f32_e32 v95, v95, v219
	v_mul_f32_e32 v96, v96, v219
	v_mul_f32_e32 v97, v97, v219
	v_mul_f32_e32 v66, v66, v219
	v_mul_f32_e32 v67, v67, v219
	v_mul_f32_e32 v68, v68, v219
	v_mul_f32_e32 v69, v69, v219
	v_mul_f32_e32 v70, v70, v219
	v_mul_f32_e32 v71, v71, v219
	v_mul_f32_e32 v72, v72, v219
	v_mul_f32_e32 v73, v73, v219
	v_mul_f32_e32 v74, v74, v219
	v_mul_f32_e32 v75, v75, v219
	v_mul_f32_e32 v76, v76, v219
	v_mul_f32_e32 v77, v77, v219
	v_mul_f32_e32 v78, v78, v219
	v_mul_f32_e32 v79, v79, v219
	v_mul_f32_e32 v80, v80, v219
	v_mul_f32_e32 v81, v81, v219
	v_mul_f32_e32 v50, v50, v219
	v_mul_f32_e32 v51, v51, v219
	v_mul_f32_e32 v52, v52, v219
	v_mul_f32_e32 v53, v53, v219
	v_mul_f32_e32 v54, v54, v219
	v_mul_f32_e32 v55, v55, v219
	v_mul_f32_e32 v56, v56, v219
	v_mul_f32_e32 v57, v57, v219
	v_mul_f32_e32 v58, v58, v219
	v_mul_f32_e32 v59, v59, v219
	v_mul_f32_e32 v60, v60, v219
	v_mul_f32_e32 v61, v61, v219
	v_mul_f32_e32 v62, v62, v219
	v_mul_f32_e32 v63, v63, v219
	v_mul_f32_e32 v64, v64, v219
	v_mul_f32_e32 v65, v65, v219
	v_mul_f32_e32 v34, v34, v219
	v_mul_f32_e32 v35, v35, v219
	v_mul_f32_e32 v36, v36, v219
	v_mul_f32_e32 v37, v37, v219
	v_mul_f32_e32 v38, v38, v219
	v_mul_f32_e32 v39, v39, v219
	v_mul_f32_e32 v40, v40, v219
	v_mul_f32_e32 v41, v41, v219
	v_mul_f32_e32 v42, v42, v219
	v_mul_f32_e32 v43, v43, v219
	v_mul_f32_e32 v44, v44, v219
	v_mul_f32_e32 v45, v45, v219
	v_mul_f32_e32 v46, v46, v219
	v_mul_f32_e32 v47, v47, v219
	v_mul_f32_e32 v48, v48, v219
	v_mul_f32_e32 v49, v49, v219
	v_mul_f32_e32 v18, v18, v219
	v_mul_f32_e32 v19, v19, v219
	v_mul_f32_e32 v20, v20, v219
	v_mul_f32_e32 v21, v21, v219
	v_mul_f32_e32 v22, v22, v219
	v_mul_f32_e32 v23, v23, v219
	v_mul_f32_e32 v24, v24, v219
	v_mul_f32_e32 v25, v25, v219
	v_mul_f32_e32 v26, v26, v219
	v_mul_f32_e32 v27, v27, v219
	v_mul_f32_e32 v28, v28, v219
	v_mul_f32_e32 v29, v29, v219
	v_mul_f32_e32 v30, v30, v219
	v_mul_f32_e32 v31, v31, v219
	v_mul_f32_e32 v32, v32, v219
	v_mul_f32_e32 v33, v33, v219

.LBB0_836:
	v_add_u32_e32 v16, s82, v182
	ds_read_b128 v[4:7], v16 offset:0
	ds_read_b128 v[194:197], v182 offset:0
	ds_read_b128 v[198:201], v182 offset:18944
	ds_read_b128 v[8:11], v16 offset:32
	ds_read_b128 v[202:205], v182 offset:32
	ds_read_b128 v[206:209], v182 offset:18976
	ds_read_b128 v[12:15], v16 offset:64
	ds_read_b128 v[210:213], v182 offset:64
	ds_read_b128 v[214:217], v182 offset:19008
	s_waitcnt lgkmcnt(6)
	v_mfma_f32_32x32x16_bf16 v[162:177], v[194:197], v[4:7], 0
	ds_read_b128 v[186:189], v16 offset:96
	ds_read_b128 v[234:237], v182 offset:96
	ds_read_b128 v[238:241], v182 offset:19040
	ds_read_b128 v[190:193], v16 offset:128
	ds_read_b128 v[242:245], v182 offset:128
	v_mfma_f32_32x32x16_bf16 v[146:161], v[198:201], v[4:7], 0
	ds_read_b128 v[246:249], v182 offset:19072
	s_waitcnt lgkmcnt(9)
	v_mfma_f32_32x32x16_bf16 v[162:177], v[202:205], v[8:11], v[162:177]
	ds_read_b128 v[4:7], v16 offset:160
	ds_read_b128 v[194:197], v182 offset:160
	v_mfma_f32_32x32x16_bf16 v[146:161], v[206:209], v[8:11], v[146:161]
	ds_read_b128 v[198:201], v182 offset:19104
	s_waitcnt lgkmcnt(9)
	v_mfma_f32_32x32x16_bf16 v[162:177], v[210:213], v[12:15], v[162:177]
	ds_read_b128 v[8:11], v16 offset:192
	ds_read_b128 v[202:205], v182 offset:192
	v_mfma_f32_32x32x16_bf16 v[146:161], v[214:217], v[12:15], v[146:161]
	ds_read_b128 v[206:209], v182 offset:19136
	s_waitcnt lgkmcnt(9)
	v_mfma_f32_32x32x16_bf16 v[162:177], v[234:237], v[186:189], v[162:177]
	ds_read_b128 v[12:15], v16 offset:224
	ds_read_b128 v[210:213], v182 offset:224
	v_mfma_f32_32x32x16_bf16 v[146:161], v[238:241], v[186:189], v[146:161]
	ds_read_b128 v[214:217], v182 offset:19168
	s_waitcnt lgkmcnt(9)
	v_mfma_f32_32x32x16_bf16 v[162:177], v[242:245], v[190:193], v[162:177]
	ds_read_b128 v[186:189], v16 offset:256
	ds_read_b128 v[234:237], v182 offset:256
	v_mfma_f32_32x32x16_bf16 v[146:161], v[246:249], v[190:193], v[146:161]
	ds_read_b128 v[238:241], v182 offset:19200
	s_waitcnt lgkmcnt(9)
	v_mfma_f32_32x32x16_bf16 v[162:177], v[194:197], v[4:7], v[162:177]
	ds_read_b128 v[190:193], v16 offset:288
	ds_read_b128 v[242:245], v182 offset:288
	v_mfma_f32_32x32x16_bf16 v[146:161], v[198:201], v[4:7], v[146:161]
	ds_read_b128 v[246:249], v182 offset:19232
	s_waitcnt lgkmcnt(9)
	v_mfma_f32_32x32x16_bf16 v[162:177], v[202:205], v[8:11], v[162:177]
	ds_read_b128 v[4:7], v16 offset:320
	ds_read_b128 v[194:197], v182 offset:320
	v_mfma_f32_32x32x16_bf16 v[146:161], v[206:209], v[8:11], v[146:161]
	ds_read_b128 v[198:201], v182 offset:19264
	s_waitcnt lgkmcnt(9)
	v_mfma_f32_32x32x16_bf16 v[162:177], v[210:213], v[12:15], v[162:177]
	ds_read_b128 v[8:11], v16 offset:352
	ds_read_b128 v[202:205], v182 offset:352
	v_mfma_f32_32x32x16_bf16 v[146:161], v[214:217], v[12:15], v[146:161]
	ds_read_b128 v[206:209], v182 offset:19296
	s_waitcnt lgkmcnt(9)
	v_mfma_f32_32x32x16_bf16 v[162:177], v[234:237], v[186:189], v[162:177]
	ds_read_b128 v[12:15], v16 offset:384
	ds_read_b128 v[210:213], v182 offset:384
	v_mfma_f32_32x32x16_bf16 v[146:161], v[238:241], v[186:189], v[146:161]
	ds_read_b128 v[214:217], v182 offset:19328
	s_waitcnt lgkmcnt(9)
	v_mfma_f32_32x32x16_bf16 v[162:177], v[242:245], v[190:193], v[162:177]
	ds_read_b128 v[186:189], v16 offset:416
	ds_read_b128 v[234:237], v182 offset:416
	v_mfma_f32_32x32x16_bf16 v[146:161], v[246:249], v[190:193], v[146:161]
	ds_read_b128 v[238:241], v182 offset:19360
	s_waitcnt lgkmcnt(9)
	v_mfma_f32_32x32x16_bf16 v[162:177], v[194:197], v[4:7], v[162:177]
	ds_read_b128 v[190:193], v16 offset:448
	ds_read_b128 v[242:245], v182 offset:448
	v_mfma_f32_32x32x16_bf16 v[146:161], v[198:201], v[4:7], v[146:161]
	ds_read_b128 v[246:249], v182 offset:19392
	s_waitcnt lgkmcnt(9)
	v_mfma_f32_32x32x16_bf16 v[162:177], v[202:205], v[8:11], v[162:177]
	ds_read_b128 v[4:7], v16 offset:480
	ds_read_b128 v[194:197], v182 offset:480
	v_mfma_f32_32x32x16_bf16 v[146:161], v[206:209], v[8:11], v[146:161]
	ds_read_b128 v[198:201], v182 offset:19424
	s_waitcnt lgkmcnt(9)
	v_mfma_f32_32x32x16_bf16 v[162:177], v[210:213], v[12:15], v[162:177]
	ds_read_b128 v[8:11], v16 offset:512
	ds_read_b128 v[202:205], v182 offset:512
	v_mfma_f32_32x32x16_bf16 v[146:161], v[214:217], v[12:15], v[146:161]
	ds_read_b128 v[206:209], v182 offset:19456
	s_waitcnt lgkmcnt(9)
	v_mfma_f32_32x32x16_bf16 v[162:177], v[234:237], v[186:189], v[162:177]
	ds_read_b128 v[12:15], v16 offset:544
	ds_read_b128 v[210:213], v182 offset:544
	v_mfma_f32_32x32x16_bf16 v[146:161], v[238:241], v[186:189], v[146:161]
	ds_read_b128 v[214:217], v182 offset:19488
	s_waitcnt lgkmcnt(9)
	v_mfma_f32_32x32x16_bf16 v[162:177], v[242:245], v[190:193], v[162:177]
	v_mfma_f32_32x32x16_bf16 v[146:161], v[246:249], v[190:193], v[146:161]
	s_waitcnt lgkmcnt(6)
	v_mfma_f32_32x32x16_bf16 v[162:177], v[194:197], v[4:7], v[162:177]
	v_mfma_f32_32x32x16_bf16 v[146:161], v[198:201], v[4:7], v[146:161]
	s_waitcnt lgkmcnt(3)
	v_mfma_f32_32x32x16_bf16 v[162:177], v[202:205], v[8:11], v[162:177]
	v_mfma_f32_32x32x16_bf16 v[146:161], v[206:209], v[8:11], v[146:161]
	s_waitcnt lgkmcnt(0)
	v_mfma_f32_32x32x16_bf16 v[162:177], v[210:213], v[12:15], v[162:177]
	v_mfma_f32_32x32x16_bf16 v[146:161], v[214:217], v[12:15], v[146:161]
	ds_read_b64_tr_b16 v[190:191], v184 offset:0
	ds_read_b64_tr_b16 v[192:193], v184 offset:4736
	ds_read_b64_tr_b16 v[194:195], v184 offset:64
	ds_read_b64_tr_b16 v[196:197], v184 offset:4800
	ds_read_b64_tr_b16 v[198:199], v184 offset:128
	ds_read_b64_tr_b16 v[200:201], v184 offset:4864
	ds_read_b64_tr_b16 v[202:203], v184 offset:192
	ds_read_b64_tr_b16 v[204:205], v184 offset:4928
	ds_read_b64_tr_b16 v[206:207], v184 offset:256
	ds_read_b64_tr_b16 v[208:209], v184 offset:4992
	ds_read_b64_tr_b16 v[210:211], v184 offset:320
	ds_read_b64_tr_b16 v[212:213], v184 offset:5056
	ds_read_b64_tr_b16 v[214:215], v184 offset:384
	ds_read_b64_tr_b16 v[216:217], v184 offset:5120
	v_max3_f32 v2, v162, v146, v163
	v_max3_f32 v17, v147, v164, v148
	v_max3_f32 v2, v2, v165, v149
	v_max3_f32 v17, v17, v166, v150
	v_max3_f32 v2, v2, v167, v151
	v_max3_f32 v17, v17, v168, v152
	v_max3_f32 v2, v2, v169, v153
	v_max3_f32 v17, v17, v170, v154
	v_max3_f32 v2, v2, v171, v155
	v_max3_f32 v17, v17, v172, v156
	v_max3_f32 v2, v2, v173, v157
	v_max3_f32 v17, v17, v174, v158
	v_max3_f32 v2, v2, v175, v159
	v_max3_f32 v17, v17, v176, v160
	v_max3_f32 v2, v2, v17, v177
	v_max_f32_e32 v2, v2, v161
	v_mov_b32_e32 v218, v2
	v_add_f32_e32 v233, 0x41000000, v178
	v_mov_b32_e32 v254, 0
	v_permlane32_swap_b32_e32 v2, v218
	v_max_f32_e32 v2, v2, v218
	v_mul_f32_e32 v2, 0x3e16c740, v2
	v_cmp_gt_f32_e32 vcc, v2, v233
	s_cbranch_vccz .Ldc1_nr0
	v_max_f32_e32 v2, v178, v2
	v_sub_f32_e32 v219, v178, v2
	v_exp_f32_e32 v219, v219
	v_mov_b32_e32 v178, v2
	v_mov_b32_e32 v218, v2
	v_mul_f32_e32 v183, v183, v219
	v_mul_f32_e32 v130, v130, v219
	v_mul_f32_e32 v131, v131, v219
	v_mul_f32_e32 v132, v132, v219
	v_mul_f32_e32 v133, v133, v219
	v_mul_f32_e32 v134, v134, v219
	v_mul_f32_e32 v135, v135, v219
	v_mul_f32_e32 v136, v136, v219
	v_mul_f32_e32 v137, v137, v219
	v_mul_f32_e32 v138, v138, v219
	v_mul_f32_e32 v139, v139, v219
	v_mul_f32_e32 v140, v140, v219
	v_mul_f32_e32 v141, v141, v219
	v_mul_f32_e32 v142, v142, v219
	v_mul_f32_e32 v143, v143, v219
	v_mul_f32_e32 v144, v144, v219
	v_mul_f32_e32 v145, v145, v219
	v_mul_f32_e32 v114, v114, v219
	v_mul_f32_e32 v115, v115, v219
	v_mul_f32_e32 v116, v116, v219
	v_mul_f32_e32 v117, v117, v219
	v_mul_f32_e32 v118, v118, v219
	v_mul_f32_e32 v119, v119, v219
	v_mul_f32_e32 v120, v120, v219
	v_mul_f32_e32 v121, v121, v219
	v_mul_f32_e32 v122, v122, v219
	v_mul_f32_e32 v123, v123, v219
	v_mul_f32_e32 v124, v124, v219
	v_mul_f32_e32 v125, v125, v219
	v_mul_f32_e32 v126, v126, v219
	v_mul_f32_e32 v127, v127, v219
	v_mul_f32_e32 v128, v128, v219
	v_mul_f32_e32 v129, v129, v219
	v_mul_f32_e32 v98, v98, v219
	v_mul_f32_e32 v99, v99, v219
	v_mul_f32_e32 v100, v100, v219
	v_mul_f32_e32 v101, v101, v219
	v_mul_f32_e32 v102, v102, v219
	v_mul_f32_e32 v103, v103, v219
	v_mul_f32_e32 v104, v104, v219
	v_mul_f32_e32 v105, v105, v219
	v_mul_f32_e32 v106, v106, v219
	v_mul_f32_e32 v107, v107, v219
	v_mul_f32_e32 v108, v108, v219
	v_mul_f32_e32 v109, v109, v219
	v_mul_f32_e32 v110, v110, v219
	v_mul_f32_e32 v111, v111, v219
	v_mul_f32_e32 v112, v112, v219
	v_mul_f32_e32 v113, v113, v219
	v_mul_f32_e32 v82, v82, v219
	v_mul_f32_e32 v83, v83, v219
	v_mul_f32_e32 v84, v84, v219
	v_mul_f32_e32 v85, v85, v219
	v_mul_f32_e32 v86, v86, v219
	v_mul_f32_e32 v87, v87, v219
	v_mul_f32_e32 v88, v88, v219
	v_mul_f32_e32 v89, v89, v219
	v_mul_f32_e32 v90, v90, v219
	v_mul_f32_e32 v91, v91, v219
	v_mul_f32_e32 v92, v92, v219
	v_mul_f32_e32 v93, v93, v219
	v_mul_f32_e32 v94, v94, v219
	v_mul_f32_e32 v95, v95, v219
	v_mul_f32_e32 v96, v96, v219
	v_mul_f32_e32 v97, v97, v219
	v_mul_f32_e32 v66, v66, v219
	v_mul_f32_e32 v67, v67, v219
	v_mul_f32_e32 v68, v68, v219
	v_mul_f32_e32 v69, v69, v219
	v_mul_f32_e32 v70, v70, v219
	v_mul_f32_e32 v71, v71, v219
	v_mul_f32_e32 v72, v72, v219
	v_mul_f32_e32 v73, v73, v219
	v_mul_f32_e32 v74, v74, v219
	v_mul_f32_e32 v75, v75, v219
	v_mul_f32_e32 v76, v76, v219
	v_mul_f32_e32 v77, v77, v219
	v_mul_f32_e32 v78, v78, v219
	v_mul_f32_e32 v79, v79, v219
	v_mul_f32_e32 v80, v80, v219
	v_mul_f32_e32 v81, v81, v219
	v_mul_f32_e32 v50, v50, v219
	v_mul_f32_e32 v51, v51, v219
	v_mul_f32_e32 v52, v52, v219
	v_mul_f32_e32 v53, v53, v219
	v_mul_f32_e32 v54, v54, v219
	v_mul_f32_e32 v55, v55, v219
	v_mul_f32_e32 v56, v56, v219
	v_mul_f32_e32 v57, v57, v219
	v_mul_f32_e32 v58, v58, v219
	v_mul_f32_e32 v59, v59, v219
	v_mul_f32_e32 v60, v60, v219
	v_mul_f32_e32 v61, v61, v219
	v_mul_f32_e32 v62, v62, v219
	v_mul_f32_e32 v63, v63, v219
	v_mul_f32_e32 v64, v64, v219
	v_mul_f32_e32 v65, v65, v219
	v_mul_f32_e32 v34, v34, v219
	v_mul_f32_e32 v35, v35, v219
	v_mul_f32_e32 v36, v36, v219
	v_mul_f32_e32 v37, v37, v219
	v_mul_f32_e32 v38, v38, v219
	v_mul_f32_e32 v39, v39, v219
	v_mul_f32_e32 v40, v40, v219
	v_mul_f32_e32 v41, v41, v219
	v_mul_f32_e32 v42, v42, v219
	v_mul_f32_e32 v43, v43, v219
	v_mul_f32_e32 v44, v44, v219
	v_mul_f32_e32 v45, v45, v219
	v_mul_f32_e32 v46, v46, v219
	v_mul_f32_e32 v47, v47, v219
	v_mul_f32_e32 v48, v48, v219
	v_mul_f32_e32 v49, v49, v219
	v_mul_f32_e32 v18, v18, v219
	v_mul_f32_e32 v19, v19, v219
	v_mul_f32_e32 v20, v20, v219
	v_mul_f32_e32 v21, v21, v219
	v_mul_f32_e32 v22, v22, v219
	v_mul_f32_e32 v23, v23, v219
	v_mul_f32_e32 v24, v24, v219
	v_mul_f32_e32 v25, v25, v219
	v_mul_f32_e32 v26, v26, v219
	v_mul_f32_e32 v27, v27, v219
	v_mul_f32_e32 v28, v28, v219
	v_mul_f32_e32 v29, v29, v219
	v_mul_f32_e32 v30, v30, v219
	v_mul_f32_e32 v31, v31, v219
	v_mul_f32_e32 v32, v32, v219
	v_mul_f32_e32 v33, v33, v219
.Ldc1_nr0:
	v_fma_f32 v162, v162, s72, -v178
	v_fma_f32 v146, v146, s72, -v178
	v_fma_f32 v163, v163, s72, -v178
	v_exp_f32_e32 v162, v162
	v_fma_f32 v147, v147, s72, -v178
	v_exp_f32_e32 v146, v146
	v_fma_f32 v164, v164, s72, -v178
	v_exp_f32_e32 v163, v163
	v_fma_f32 v148, v148, s72, -v178
	v_exp_f32_e32 v147, v147
	v_fma_f32 v165, v165, s72, -v178
	v_add_f32_e32 v218, v162, v146
	v_exp_f32_e32 v164, v164
	v_fma_f32 v149, v149, s72, -v178
	v_exp_f32_e32 v148, v148
	v_cvt_pk_bf16_f32 v4, v162, v163
	v_fma_f32 v166, v166, s72, -v178
	v_add_f32_e32 v233, v163, v147
	v_exp_f32_e32 v165, v165
	v_add_f32_e32 v254, v254, v218
	v_cvt_pk_bf16_f32 v12, v146, v147
	v_fma_f32 v150, v150, s72, -v178
	v_exp_f32_e32 v149, v149
	v_fma_f32 v167, v167, s72, -v178
	v_add_f32_e32 v17, v164, v148
	v_exp_f32_e32 v166, v166
	v_add_f32_e32 v254, v254, v233
	v_fma_f32 v151, v151, s72, -v178
	v_exp_f32_e32 v150, v150
	v_cvt_pk_bf16_f32 v5, v164, v165
	v_fma_f32 v168, v168, s72, -v178
	v_add_f32_e32 v219, v165, v149
	v_exp_f32_e32 v167, v167
	v_add_f32_e32 v254, v254, v17
	v_cvt_pk_bf16_f32 v13, v148, v149
	v_fma_f32 v152, v152, s72, -v178
	v_exp_f32_e32 v151, v151
	v_fma_f32 v169, v169, s72, -v178
	v_add_f32_e32 v218, v166, v150
	v_exp_f32_e32 v168, v168
	v_add_f32_e32 v254, v254, v219
	v_fma_f32 v153, v153, s72, -v178
	v_exp_f32_e32 v152, v152
	v_cvt_pk_bf16_f32 v6, v166, v167
	v_fma_f32 v170, v170, s72, -v178
	v_add_f32_e32 v233, v167, v151
	v_exp_f32_e32 v169, v169
	v_add_f32_e32 v254, v254, v218
	v_cvt_pk_bf16_f32 v14, v150, v151
	v_fma_f32 v154, v154, s72, -v178
	v_exp_f32_e32 v153, v153
	v_fma_f32 v171, v171, s72, -v178
	v_add_f32_e32 v17, v168, v152
	v_exp_f32_e32 v170, v170
	v_add_f32_e32 v254, v254, v233
	v_fma_f32 v155, v155, s72, -v178
	v_exp_f32_e32 v154, v154
	v_cvt_pk_bf16_f32 v7, v168, v169
	v_fma_f32 v172, v172, s72, -v178
	v_add_f32_e32 v219, v169, v153
	v_exp_f32_e32 v171, v171
	v_add_f32_e32 v254, v254, v17
	v_cvt_pk_bf16_f32 v15, v152, v153
	v_fma_f32 v156, v156, s72, -v178
	v_exp_f32_e32 v155, v155
	v_fma_f32 v173, v173, s72, -v178
	v_add_f32_e32 v218, v170, v154
	v_exp_f32_e32 v172, v172
	v_add_f32_e32 v254, v254, v219
	v_fma_f32 v157, v157, s72, -v178
	v_exp_f32_e32 v156, v156
	v_cvt_pk_bf16_f32 v8, v170, v171
	v_fma_f32 v174, v174, s72, -v178
	v_add_f32_e32 v233, v171, v155
	v_exp_f32_e32 v173, v173
	v_add_f32_e32 v254, v254, v218
	v_cvt_pk_bf16_f32 v186, v154, v155
	v_fma_f32 v158, v158, s72, -v178
	v_exp_f32_e32 v157, v157
	v_fma_f32 v175, v175, s72, -v178
	v_add_f32_e32 v17, v172, v156
	v_exp_f32_e32 v174, v174
	v_add_f32_e32 v254, v254, v233
	v_fma_f32 v159, v159, s72, -v178
	v_exp_f32_e32 v158, v158
	v_cvt_pk_bf16_f32 v9, v172, v173
	v_fma_f32 v176, v176, s72, -v178
	v_add_f32_e32 v219, v173, v157
	v_exp_f32_e32 v175, v175
	v_add_f32_e32 v254, v254, v17
	v_cvt_pk_bf16_f32 v187, v156, v157
	v_fma_f32 v160, v160, s72, -v178
	v_exp_f32_e32 v159, v159
	v_fma_f32 v177, v177, s72, -v178
	v_add_f32_e32 v218, v174, v158
	v_exp_f32_e32 v176, v176
	v_add_f32_e32 v254, v254, v219
	v_fma_f32 v161, v161, s72, -v178
	v_exp_f32_e32 v160, v160
	v_cvt_pk_bf16_f32 v10, v174, v175
	v_add_f32_e32 v233, v175, v159
	v_exp_f32_e32 v177, v177
	v_add_f32_e32 v254, v254, v218
	v_cvt_pk_bf16_f32 v188, v158, v159
	v_exp_f32_e32 v161, v161
	v_add_f32_e32 v17, v176, v160
	v_add_f32_e32 v254, v254, v233
	v_cvt_pk_bf16_f32 v11, v176, v177
	v_add_f32_e32 v219, v177, v161
	v_add_f32_e32 v254, v254, v17
	v_cvt_pk_bf16_f32 v189, v160, v161
	v_add_f32_e32 v254, v254, v219
	v_add_f32_e32 v183, v183, v254
	s_waitcnt lgkmcnt(12)
	v_mfma_f32_32x32x16_bf16 v[130:145], v[190:193], v[4:7], v[130:145]
	ds_read_b64_tr_b16 v[234:235], v184 offset:448
	ds_read_b64_tr_b16 v[236:237], v184 offset:5184
	s_waitcnt lgkmcnt(12)
	v_mfma_f32_32x32x16_bf16 v[114:129], v[194:197], v[4:7], v[114:129]
	ds_read_b64_tr_b16 v[238:239], v184 offset:9472
	ds_read_b64_tr_b16 v[240:241], v184 offset:14208
	s_waitcnt lgkmcnt(12)
	v_mfma_f32_32x32x16_bf16 v[98:113], v[198:201], v[4:7], v[98:113]
	ds_read_b64_tr_b16 v[242:243], v184 offset:9536
	ds_read_b64_tr_b16 v[244:245], v184 offset:14272
	s_waitcnt lgkmcnt(12)
	v_mfma_f32_32x32x16_bf16 v[82:97], v[202:205], v[4:7], v[82:97]
	ds_read_b64_tr_b16 v[246:247], v184 offset:9600
	ds_read_b64_tr_b16 v[248:249], v184 offset:14336
	s_waitcnt lgkmcnt(12)
	v_mfma_f32_32x32x16_bf16 v[66:81], v[206:209], v[4:7], v[66:81]
	ds_read_b64_tr_b16 v[250:251], v184 offset:9664
	ds_read_b64_tr_b16 v[252:253], v184 offset:14400
	s_waitcnt lgkmcnt(12)
	v_mfma_f32_32x32x16_bf16 v[50:65], v[210:213], v[4:7], v[50:65]
	ds_read_b64_tr_b16 v[190:191], v184 offset:9728
	ds_read_b64_tr_b16 v[192:193], v184 offset:14464
	s_waitcnt lgkmcnt(12)
	v_mfma_f32_32x32x16_bf16 v[34:49], v[214:217], v[4:7], v[34:49]
	ds_read_b64_tr_b16 v[194:195], v184 offset:9792
	ds_read_b64_tr_b16 v[196:197], v184 offset:14528
	s_waitcnt lgkmcnt(12)
	v_mfma_f32_32x32x16_bf16 v[18:33], v[234:237], v[4:7], v[18:33]
	ds_read_b64_tr_b16 v[198:199], v184 offset:9856
	ds_read_b64_tr_b16 v[200:201], v184 offset:14592
	s_waitcnt lgkmcnt(12)
	v_mfma_f32_32x32x16_bf16 v[130:145], v[238:241], v[8:11], v[130:145]
	ds_read_b64_tr_b16 v[202:203], v184 offset:9920
	ds_read_b64_tr_b16 v[204:205], v184 offset:14656
	s_waitcnt lgkmcnt(12)
	v_mfma_f32_32x32x16_bf16 v[114:129], v[242:245], v[8:11], v[114:129]
	ds_read_b64_tr_b16 v[206:207], v184 offset:18944
	ds_read_b64_tr_b16 v[208:209], v184 offset:23680
	s_waitcnt lgkmcnt(12)
	v_mfma_f32_32x32x16_bf16 v[98:113], v[246:249], v[8:11], v[98:113]
	ds_read_b64_tr_b16 v[210:211], v184 offset:19008
	ds_read_b64_tr_b16 v[212:213], v184 offset:23744
	s_waitcnt lgkmcnt(12)
	v_mfma_f32_32x32x16_bf16 v[82:97], v[250:253], v[8:11], v[82:97]
	ds_read_b64_tr_b16 v[214:215], v184 offset:19072
	ds_read_b64_tr_b16 v[216:217], v184 offset:23808
	s_waitcnt lgkmcnt(12)
	v_mfma_f32_32x32x16_bf16 v[66:81], v[190:193], v[8:11], v[66:81]
	ds_read_b64_tr_b16 v[234:235], v184 offset:19136
	ds_read_b64_tr_b16 v[236:237], v184 offset:23872
	s_waitcnt lgkmcnt(12)
	v_mfma_f32_32x32x16_bf16 v[50:65], v[194:197], v[8:11], v[50:65]
	ds_read_b64_tr_b16 v[238:239], v184 offset:19200
	ds_read_b64_tr_b16 v[240:241], v184 offset:23936
	s_waitcnt lgkmcnt(12)
	v_mfma_f32_32x32x16_bf16 v[34:49], v[198:201], v[8:11], v[34:49]
	ds_read_b64_tr_b16 v[242:243], v184 offset:19264
	ds_read_b64_tr_b16 v[244:245], v184 offset:24000
	s_waitcnt lgkmcnt(12)
	v_mfma_f32_32x32x16_bf16 v[18:33], v[202:205], v[8:11], v[18:33]
	ds_read_b64_tr_b16 v[246:247], v184 offset:19328
	ds_read_b64_tr_b16 v[248:249], v184 offset:24064
	s_waitcnt lgkmcnt(12)
	v_mfma_f32_32x32x16_bf16 v[130:145], v[206:209], v[12:15], v[130:145]
	ds_read_b64_tr_b16 v[250:251], v184 offset:19392
	ds_read_b64_tr_b16 v[252:253], v184 offset:24128
	s_waitcnt lgkmcnt(12)
	v_mfma_f32_32x32x16_bf16 v[114:129], v[210:213], v[12:15], v[114:129]
	ds_read_b64_tr_b16 v[190:191], v184 offset:28416
	ds_read_b64_tr_b16 v[192:193], v184 offset:33152
	s_waitcnt lgkmcnt(12)
	v_mfma_f32_32x32x16_bf16 v[98:113], v[214:217], v[12:15], v[98:113]
	ds_read_b64_tr_b16 v[194:195], v184 offset:28480
	ds_read_b64_tr_b16 v[196:197], v184 offset:33216
	s_waitcnt lgkmcnt(12)
	v_mfma_f32_32x32x16_bf16 v[82:97], v[234:237], v[12:15], v[82:97]
	ds_read_b64_tr_b16 v[198:199], v184 offset:28544
	ds_read_b64_tr_b16 v[200:201], v184 offset:33280
	s_waitcnt lgkmcnt(12)
	v_mfma_f32_32x32x16_bf16 v[66:81], v[238:241], v[12:15], v[66:81]
	ds_read_b64_tr_b16 v[202:203], v184 offset:28608
	ds_read_b64_tr_b16 v[204:205], v184 offset:33344
	s_waitcnt lgkmcnt(12)
	v_mfma_f32_32x32x16_bf16 v[50:65], v[242:245], v[12:15], v[50:65]
	ds_read_b64_tr_b16 v[206:207], v184 offset:28672
	ds_read_b64_tr_b16 v[208:209], v184 offset:33408
	s_waitcnt lgkmcnt(12)
	v_mfma_f32_32x32x16_bf16 v[34:49], v[246:249], v[12:15], v[34:49]
	ds_read_b64_tr_b16 v[210:211], v184 offset:28736
	ds_read_b64_tr_b16 v[212:213], v184 offset:33472
	s_waitcnt lgkmcnt(12)
	v_mfma_f32_32x32x16_bf16 v[18:33], v[250:253], v[12:15], v[18:33]
	ds_read_b64_tr_b16 v[214:215], v184 offset:28800
	ds_read_b64_tr_b16 v[216:217], v184 offset:33536
	s_waitcnt lgkmcnt(12)
	v_mfma_f32_32x32x16_bf16 v[130:145], v[190:193], v[186:189], v[130:145]
	ds_read_b64_tr_b16 v[234:235], v184 offset:28864
	ds_read_b64_tr_b16 v[236:237], v184 offset:33600
	s_waitcnt lgkmcnt(12)
	v_mfma_f32_32x32x16_bf16 v[114:129], v[194:197], v[186:189], v[114:129]
	s_waitcnt lgkmcnt(10)
	v_mfma_f32_32x32x16_bf16 v[98:113], v[198:201], v[186:189], v[98:113]
	s_waitcnt lgkmcnt(8)
	v_mfma_f32_32x32x16_bf16 v[82:97], v[202:205], v[186:189], v[82:97]
	s_waitcnt lgkmcnt(6)
	v_mfma_f32_32x32x16_bf16 v[66:81], v[206:209], v[186:189], v[66:81]
	s_waitcnt lgkmcnt(4)
	v_mfma_f32_32x32x16_bf16 v[50:65], v[210:213], v[186:189], v[50:65]
	s_waitcnt lgkmcnt(2)
	v_mfma_f32_32x32x16_bf16 v[34:49], v[214:217], v[186:189], v[34:49]
	s_waitcnt lgkmcnt(0)
	v_mfma_f32_32x32x16_bf16 v[18:33], v[234:237], v[186:189], v[18:33]
	s_waitcnt lgkmcnt(0)
	s_barrier
	ds_read_b128 v[4:7], v16 offset:0
	ds_read_b128 v[194:197], v182 offset:37888
	ds_read_b128 v[198:201], v182 offset:56832
	ds_read_b128 v[8:11], v16 offset:32
	ds_read_b128 v[202:205], v182 offset:37920
	ds_read_b128 v[206:209], v182 offset:56864
	ds_read_b128 v[12:15], v16 offset:64
	ds_read_b128 v[210:213], v182 offset:37952
	ds_read_b128 v[214:217], v182 offset:56896
	s_waitcnt lgkmcnt(6)
	v_mfma_f32_32x32x16_bf16 v[162:177], v[194:197], v[4:7], 0
	ds_read_b128 v[186:189], v16 offset:96
	ds_read_b128 v[234:237], v182 offset:37984
	ds_read_b128 v[238:241], v182 offset:56928
	ds_read_b128 v[190:193], v16 offset:128
	ds_read_b128 v[242:245], v182 offset:38016
	v_mfma_f32_32x32x16_bf16 v[146:161], v[198:201], v[4:7], 0
	ds_read_b128 v[246:249], v182 offset:56960
	s_waitcnt lgkmcnt(9)
	v_mfma_f32_32x32x16_bf16 v[162:177], v[202:205], v[8:11], v[162:177]
	ds_read_b128 v[4:7], v16 offset:160
	ds_read_b128 v[194:197], v182 offset:38048
	v_mfma_f32_32x32x16_bf16 v[146:161], v[206:209], v[8:11], v[146:161]
	ds_read_b128 v[198:201], v182 offset:56992
	s_waitcnt lgkmcnt(9)
	v_mfma_f32_32x32x16_bf16 v[162:177], v[210:213], v[12:15], v[162:177]
	ds_read_b128 v[8:11], v16 offset:192
	ds_read_b128 v[202:205], v182 offset:38080
	v_mfma_f32_32x32x16_bf16 v[146:161], v[214:217], v[12:15], v[146:161]
	ds_read_b128 v[206:209], v182 offset:57024
	s_waitcnt lgkmcnt(9)
	v_mfma_f32_32x32x16_bf16 v[162:177], v[234:237], v[186:189], v[162:177]
	ds_read_b128 v[12:15], v16 offset:224
	ds_read_b128 v[210:213], v182 offset:38112
	v_mfma_f32_32x32x16_bf16 v[146:161], v[238:241], v[186:189], v[146:161]
	ds_read_b128 v[214:217], v182 offset:57056
	s_waitcnt lgkmcnt(9)
	v_mfma_f32_32x32x16_bf16 v[162:177], v[242:245], v[190:193], v[162:177]
	ds_read_b128 v[186:189], v16 offset:256
	ds_read_b128 v[234:237], v182 offset:38144
	v_mfma_f32_32x32x16_bf16 v[146:161], v[246:249], v[190:193], v[146:161]
	ds_read_b128 v[238:241], v182 offset:57088
	s_waitcnt lgkmcnt(9)
	v_mfma_f32_32x32x16_bf16 v[162:177], v[194:197], v[4:7], v[162:177]
	ds_read_b128 v[190:193], v16 offset:288
	ds_read_b128 v[242:245], v182 offset:38176
	v_mfma_f32_32x32x16_bf16 v[146:161], v[198:201], v[4:7], v[146:161]
	ds_read_b128 v[246:249], v182 offset:57120
	s_waitcnt lgkmcnt(9)
	v_mfma_f32_32x32x16_bf16 v[162:177], v[202:205], v[8:11], v[162:177]
	ds_read_b128 v[4:7], v16 offset:320
	ds_read_b128 v[194:197], v182 offset:38208
	v_mfma_f32_32x32x16_bf16 v[146:161], v[206:209], v[8:11], v[146:161]
	ds_read_b128 v[198:201], v182 offset:57152
	s_waitcnt lgkmcnt(9)
	v_mfma_f32_32x32x16_bf16 v[162:177], v[210:213], v[12:15], v[162:177]
	ds_read_b128 v[8:11], v16 offset:352
	ds_read_b128 v[202:205], v182 offset:38240
	v_mfma_f32_32x32x16_bf16 v[146:161], v[214:217], v[12:15], v[146:161]
	ds_read_b128 v[206:209], v182 offset:57184
	s_waitcnt lgkmcnt(9)
	v_mfma_f32_32x32x16_bf16 v[162:177], v[234:237], v[186:189], v[162:177]
	ds_read_b128 v[12:15], v16 offset:384
	ds_read_b128 v[210:213], v182 offset:38272
	v_mfma_f32_32x32x16_bf16 v[146:161], v[238:241], v[186:189], v[146:161]
	ds_read_b128 v[214:217], v182 offset:57216
	s_waitcnt lgkmcnt(9)
	v_mfma_f32_32x32x16_bf16 v[162:177], v[242:245], v[190:193], v[162:177]
	ds_read_b128 v[186:189], v16 offset:416
	ds_read_b128 v[234:237], v182 offset:38304
	v_mfma_f32_32x32x16_bf16 v[146:161], v[246:249], v[190:193], v[146:161]
	ds_read_b128 v[238:241], v182 offset:57248
	s_waitcnt lgkmcnt(9)
	v_mfma_f32_32x32x16_bf16 v[162:177], v[194:197], v[4:7], v[162:177]
	ds_read_b128 v[190:193], v16 offset:448
	ds_read_b128 v[242:245], v182 offset:38336
	v_mfma_f32_32x32x16_bf16 v[146:161], v[198:201], v[4:7], v[146:161]
	ds_read_b128 v[246:249], v182 offset:57280
	s_waitcnt lgkmcnt(9)
	v_mfma_f32_32x32x16_bf16 v[162:177], v[202:205], v[8:11], v[162:177]
	ds_read_b128 v[4:7], v16 offset:480
	ds_read_b128 v[194:197], v182 offset:38368
	v_mfma_f32_32x32x16_bf16 v[146:161], v[206:209], v[8:11], v[146:161]
	ds_read_b128 v[198:201], v182 offset:57312
	s_waitcnt lgkmcnt(9)
	v_mfma_f32_32x32x16_bf16 v[162:177], v[210:213], v[12:15], v[162:177]
	ds_read_b128 v[8:11], v16 offset:512
	ds_read_b128 v[202:205], v182 offset:38400
	v_mfma_f32_32x32x16_bf16 v[146:161], v[214:217], v[12:15], v[146:161]
	ds_read_b128 v[206:209], v182 offset:57344
	s_waitcnt lgkmcnt(9)
	v_mfma_f32_32x32x16_bf16 v[162:177], v[234:237], v[186:189], v[162:177]
	ds_read_b128 v[12:15], v16 offset:544
	ds_read_b128 v[210:213], v182 offset:38432
	v_mfma_f32_32x32x16_bf16 v[146:161], v[238:241], v[186:189], v[146:161]
	ds_read_b128 v[214:217], v182 offset:57376
	s_waitcnt lgkmcnt(9)
	v_mfma_f32_32x32x16_bf16 v[162:177], v[242:245], v[190:193], v[162:177]
	v_mfma_f32_32x32x16_bf16 v[146:161], v[246:249], v[190:193], v[146:161]
	s_waitcnt lgkmcnt(6)
	v_mfma_f32_32x32x16_bf16 v[162:177], v[194:197], v[4:7], v[162:177]
	v_mfma_f32_32x32x16_bf16 v[146:161], v[198:201], v[4:7], v[146:161]
	s_waitcnt lgkmcnt(3)
	v_mfma_f32_32x32x16_bf16 v[162:177], v[202:205], v[8:11], v[162:177]
	v_mfma_f32_32x32x16_bf16 v[146:161], v[206:209], v[8:11], v[146:161]
	s_waitcnt lgkmcnt(0)
	v_mfma_f32_32x32x16_bf16 v[162:177], v[210:213], v[12:15], v[162:177]
	v_mfma_f32_32x32x16_bf16 v[146:161], v[214:217], v[12:15], v[146:161]
	ds_read_b64_tr_b16 v[190:191], v185 offset:0
	ds_read_b64_tr_b16 v[192:193], v185 offset:4736
	ds_read_b64_tr_b16 v[194:195], v185 offset:64
	ds_read_b64_tr_b16 v[196:197], v185 offset:4800
	ds_read_b64_tr_b16 v[198:199], v185 offset:128
	ds_read_b64_tr_b16 v[200:201], v185 offset:4864
	ds_read_b64_tr_b16 v[202:203], v185 offset:192
	ds_read_b64_tr_b16 v[204:205], v185 offset:4928
	ds_read_b64_tr_b16 v[206:207], v185 offset:256
	ds_read_b64_tr_b16 v[208:209], v185 offset:4992
	ds_read_b64_tr_b16 v[210:211], v185 offset:320
	ds_read_b64_tr_b16 v[212:213], v185 offset:5056
	ds_read_b64_tr_b16 v[214:215], v185 offset:384
	ds_read_b64_tr_b16 v[216:217], v185 offset:5120
	v_max3_f32 v2, v162, v146, v163
	v_max3_f32 v17, v147, v164, v148
	v_max3_f32 v2, v2, v165, v149
	v_max3_f32 v17, v17, v166, v150
	v_max3_f32 v2, v2, v167, v151
	v_max3_f32 v17, v17, v168, v152
	v_max3_f32 v2, v2, v169, v153
	v_max3_f32 v17, v17, v170, v154
	v_max3_f32 v2, v2, v171, v155
	v_max3_f32 v17, v17, v172, v156
	v_max3_f32 v2, v2, v173, v157
	v_max3_f32 v17, v17, v174, v158
	v_max3_f32 v2, v2, v175, v159
	v_max3_f32 v17, v17, v176, v160
	v_max3_f32 v2, v2, v17, v177
	v_max_f32_e32 v2, v2, v161
	v_mov_b32_e32 v218, v2
	v_add_f32_e32 v233, 0x41000000, v178
	v_mov_b32_e32 v254, 0
	v_permlane32_swap_b32_e32 v2, v218
	v_max_f32_e32 v2, v2, v218
	v_mul_f32_e32 v2, 0x3e16c740, v2
	v_cmp_gt_f32_e32 vcc, v2, v233
	s_cbranch_vccz .Ldc1_nr1
	v_max_f32_e32 v2, v178, v2
	v_sub_f32_e32 v219, v178, v2
	v_exp_f32_e32 v219, v219
	v_mov_b32_e32 v178, v2
	v_mov_b32_e32 v218, v2
	v_mul_f32_e32 v183, v183, v219
	v_mul_f32_e32 v130, v130, v219
	v_mul_f32_e32 v131, v131, v219
	v_mul_f32_e32 v132, v132, v219
	v_mul_f32_e32 v133, v133, v219
	v_mul_f32_e32 v134, v134, v219
	v_mul_f32_e32 v135, v135, v219
	v_mul_f32_e32 v136, v136, v219
	v_mul_f32_e32 v137, v137, v219
	v_mul_f32_e32 v138, v138, v219
	v_mul_f32_e32 v139, v139, v219
	v_mul_f32_e32 v140, v140, v219
	v_mul_f32_e32 v141, v141, v219
	v_mul_f32_e32 v142, v142, v219
	v_mul_f32_e32 v143, v143, v219
	v_mul_f32_e32 v144, v144, v219
	v_mul_f32_e32 v145, v145, v219
	v_mul_f32_e32 v114, v114, v219
	v_mul_f32_e32 v115, v115, v219
	v_mul_f32_e32 v116, v116, v219
	v_mul_f32_e32 v117, v117, v219
	v_mul_f32_e32 v118, v118, v219
	v_mul_f32_e32 v119, v119, v219
	v_mul_f32_e32 v120, v120, v219
	v_mul_f32_e32 v121, v121, v219
	v_mul_f32_e32 v122, v122, v219
	v_mul_f32_e32 v123, v123, v219
	v_mul_f32_e32 v124, v124, v219
	v_mul_f32_e32 v125, v125, v219
	v_mul_f32_e32 v126, v126, v219
	v_mul_f32_e32 v127, v127, v219
	v_mul_f32_e32 v128, v128, v219
	v_mul_f32_e32 v129, v129, v219
	v_mul_f32_e32 v98, v98, v219
	v_mul_f32_e32 v99, v99, v219
	v_mul_f32_e32 v100, v100, v219
	v_mul_f32_e32 v101, v101, v219
	v_mul_f32_e32 v102, v102, v219
	v_mul_f32_e32 v103, v103, v219
	v_mul_f32_e32 v104, v104, v219
	v_mul_f32_e32 v105, v105, v219
	v_mul_f32_e32 v106, v106, v219
	v_mul_f32_e32 v107, v107, v219
	v_mul_f32_e32 v108, v108, v219
	v_mul_f32_e32 v109, v109, v219
	v_mul_f32_e32 v110, v110, v219
	v_mul_f32_e32 v111, v111, v219
	v_mul_f32_e32 v112, v112, v219
	v_mul_f32_e32 v113, v113, v219
	v_mul_f32_e32 v82, v82, v219
	v_mul_f32_e32 v83, v83, v219
	v_mul_f32_e32 v84, v84, v219
	v_mul_f32_e32 v85, v85, v219
	v_mul_f32_e32 v86, v86, v219
	v_mul_f32_e32 v87, v87, v219
	v_mul_f32_e32 v88, v88, v219
	v_mul_f32_e32 v89, v89, v219
	v_mul_f32_e32 v90, v90, v219
	v_mul_f32_e32 v91, v91, v219
	v_mul_f32_e32 v92, v92, v219
	v_mul_f32_e32 v93, v93, v219
	v_mul_f32_e32 v94, v94, v219
	v_mul_f32_e32 v95, v95, v219
	v_mul_f32_e32 v96, v96, v219
	v_mul_f32_e32 v97, v97, v219
	v_mul_f32_e32 v66, v66, v219
	v_mul_f32_e32 v67, v67, v219
	v_mul_f32_e32 v68, v68, v219
	v_mul_f32_e32 v69, v69, v219
	v_mul_f32_e32 v70, v70, v219
	v_mul_f32_e32 v71, v71, v219
	v_mul_f32_e32 v72, v72, v219
	v_mul_f32_e32 v73, v73, v219
	v_mul_f32_e32 v74, v74, v219
	v_mul_f32_e32 v75, v75, v219
	v_mul_f32_e32 v76, v76, v219
	v_mul_f32_e32 v77, v77, v219
	v_mul_f32_e32 v78, v78, v219
	v_mul_f32_e32 v79, v79, v219
	v_mul_f32_e32 v80, v80, v219
	v_mul_f32_e32 v81, v81, v219
	v_mul_f32_e32 v50, v50, v219
	v_mul_f32_e32 v51, v51, v219
	v_mul_f32_e32 v52, v52, v219
	v_mul_f32_e32 v53, v53, v219
	v_mul_f32_e32 v54, v54, v219
	v_mul_f32_e32 v55, v55, v219
	v_mul_f32_e32 v56, v56, v219
	v_mul_f32_e32 v57, v57, v219
	v_mul_f32_e32 v58, v58, v219
	v_mul_f32_e32 v59, v59, v219
	v_mul_f32_e32 v60, v60, v219
	v_mul_f32_e32 v61, v61, v219
	v_mul_f32_e32 v62, v62, v219
	v_mul_f32_e32 v63, v63, v219
	v_mul_f32_e32 v64, v64, v219
	v_mul_f32_e32 v65, v65, v219
	v_mul_f32_e32 v34, v34, v219
	v_mul_f32_e32 v35, v35, v219
	v_mul_f32_e32 v36, v36, v219
	v_mul_f32_e32 v37, v37, v219
	v_mul_f32_e32 v38, v38, v219
	v_mul_f32_e32 v39, v39, v219
	v_mul_f32_e32 v40, v40, v219
	v_mul_f32_e32 v41, v41, v219
	v_mul_f32_e32 v42, v42, v219
	v_mul_f32_e32 v43, v43, v219
	v_mul_f32_e32 v44, v44, v219
	v_mul_f32_e32 v45, v45, v219
	v_mul_f32_e32 v46, v46, v219
	v_mul_f32_e32 v47, v47, v219
	v_mul_f32_e32 v48, v48, v219
	v_mul_f32_e32 v49, v49, v219
	v_mul_f32_e32 v18, v18, v219
	v_mul_f32_e32 v19, v19, v219
	v_mul_f32_e32 v20, v20, v219
	v_mul_f32_e32 v21, v21, v219
	v_mul_f32_e32 v22, v22, v219
	v_mul_f32_e32 v23, v23, v219
	v_mul_f32_e32 v24, v24, v219
	v_mul_f32_e32 v25, v25, v219
	v_mul_f32_e32 v26, v26, v219
	v_mul_f32_e32 v27, v27, v219
	v_mul_f32_e32 v28, v28, v219
	v_mul_f32_e32 v29, v29, v219
	v_mul_f32_e32 v30, v30, v219
	v_mul_f32_e32 v31, v31, v219
	v_mul_f32_e32 v32, v32, v219
	v_mul_f32_e32 v33, v33, v219

.LBB0_911:
	v_add_u32_e32 v16, s50, v182
	ds_read_b128 v[4:7], v16 offset:0
	ds_read_b128 v[194:197], v182 offset:0
	ds_read_b128 v[198:201], v182 offset:18944
	ds_read_b128 v[8:11], v16 offset:32
	ds_read_b128 v[202:205], v182 offset:32
	ds_read_b128 v[206:209], v182 offset:18976
	ds_read_b128 v[12:15], v16 offset:64
	ds_read_b128 v[210:213], v182 offset:64
	ds_read_b128 v[214:217], v182 offset:19008
	s_waitcnt lgkmcnt(6)
	v_mfma_f32_32x32x16_bf16 v[162:177], v[194:197], v[4:7], 0
	ds_read_b128 v[186:189], v16 offset:96
	ds_read_b128 v[234:237], v182 offset:96
	ds_read_b128 v[238:241], v182 offset:19040
	ds_read_b128 v[190:193], v16 offset:128
	ds_read_b128 v[242:245], v182 offset:128
	v_mfma_f32_32x32x16_bf16 v[146:161], v[198:201], v[4:7], 0
	ds_read_b128 v[246:249], v182 offset:19072
	s_waitcnt lgkmcnt(9)
	v_mfma_f32_32x32x16_bf16 v[162:177], v[202:205], v[8:11], v[162:177]
	ds_read_b128 v[4:7], v16 offset:160
	ds_read_b128 v[194:197], v182 offset:160
	v_mfma_f32_32x32x16_bf16 v[146:161], v[206:209], v[8:11], v[146:161]
	ds_read_b128 v[198:201], v182 offset:19104
	s_waitcnt lgkmcnt(9)
	v_mfma_f32_32x32x16_bf16 v[162:177], v[210:213], v[12:15], v[162:177]
	ds_read_b128 v[8:11], v16 offset:192
	ds_read_b128 v[202:205], v182 offset:192
	v_mfma_f32_32x32x16_bf16 v[146:161], v[214:217], v[12:15], v[146:161]
	ds_read_b128 v[206:209], v182 offset:19136
	s_waitcnt lgkmcnt(9)
	v_mfma_f32_32x32x16_bf16 v[162:177], v[234:237], v[186:189], v[162:177]
	ds_read_b128 v[12:15], v16 offset:224
	ds_read_b128 v[210:213], v182 offset:224
	v_mfma_f32_32x32x16_bf16 v[146:161], v[238:241], v[186:189], v[146:161]
	ds_read_b128 v[214:217], v182 offset:19168
	s_waitcnt lgkmcnt(9)
	v_mfma_f32_32x32x16_bf16 v[162:177], v[242:245], v[190:193], v[162:177]
	ds_read_b128 v[186:189], v16 offset:256
	ds_read_b128 v[234:237], v182 offset:256
	v_mfma_f32_32x32x16_bf16 v[146:161], v[246:249], v[190:193], v[146:161]
	ds_read_b128 v[238:241], v182 offset:19200
	s_waitcnt lgkmcnt(9)
	v_mfma_f32_32x32x16_bf16 v[162:177], v[194:197], v[4:7], v[162:177]
	ds_read_b128 v[190:193], v16 offset:288
	ds_read_b128 v[242:245], v182 offset:288
	v_mfma_f32_32x32x16_bf16 v[146:161], v[198:201], v[4:7], v[146:161]
	ds_read_b128 v[246:249], v182 offset:19232
	s_waitcnt lgkmcnt(9)
	v_mfma_f32_32x32x16_bf16 v[162:177], v[202:205], v[8:11], v[162:177]
	ds_read_b128 v[4:7], v16 offset:320
	ds_read_b128 v[194:197], v182 offset:320
	v_mfma_f32_32x32x16_bf16 v[146:161], v[206:209], v[8:11], v[146:161]
	ds_read_b128 v[198:201], v182 offset:19264
	s_waitcnt lgkmcnt(9)
	v_mfma_f32_32x32x16_bf16 v[162:177], v[210:213], v[12:15], v[162:177]
	ds_read_b128 v[8:11], v16 offset:352
	ds_read_b128 v[202:205], v182 offset:352
	v_mfma_f32_32x32x16_bf16 v[146:161], v[214:217], v[12:15], v[146:161]
	ds_read_b128 v[206:209], v182 offset:19296
	s_waitcnt lgkmcnt(9)
	v_mfma_f32_32x32x16_bf16 v[162:177], v[234:237], v[186:189], v[162:177]
	ds_read_b128 v[12:15], v16 offset:384
	ds_read_b128 v[210:213], v182 offset:384
	v_mfma_f32_32x32x16_bf16 v[146:161], v[238:241], v[186:189], v[146:161]
	ds_read_b128 v[214:217], v182 offset:19328
	s_waitcnt lgkmcnt(9)
	v_mfma_f32_32x32x16_bf16 v[162:177], v[242:245], v[190:193], v[162:177]
	ds_read_b128 v[186:189], v16 offset:416
	ds_read_b128 v[234:237], v182 offset:416
	v_mfma_f32_32x32x16_bf16 v[146:161], v[246:249], v[190:193], v[146:161]
	ds_read_b128 v[238:241], v182 offset:19360
	s_waitcnt lgkmcnt(9)
	v_mfma_f32_32x32x16_bf16 v[162:177], v[194:197], v[4:7], v[162:177]
	ds_read_b128 v[190:193], v16 offset:448
	ds_read_b128 v[242:245], v182 offset:448
	v_mfma_f32_32x32x16_bf16 v[146:161], v[198:201], v[4:7], v[146:161]
	ds_read_b128 v[246:249], v182 offset:19392
	s_waitcnt lgkmcnt(9)
	v_mfma_f32_32x32x16_bf16 v[162:177], v[202:205], v[8:11], v[162:177]
	ds_read_b128 v[4:7], v16 offset:480
	ds_read_b128 v[194:197], v182 offset:480
	v_mfma_f32_32x32x16_bf16 v[146:161], v[206:209], v[8:11], v[146:161]
	ds_read_b128 v[198:201], v182 offset:19424
	s_waitcnt lgkmcnt(9)
	v_mfma_f32_32x32x16_bf16 v[162:177], v[210:213], v[12:15], v[162:177]
	ds_read_b128 v[8:11], v16 offset:512
	ds_read_b128 v[202:205], v182 offset:512
	v_mfma_f32_32x32x16_bf16 v[146:161], v[214:217], v[12:15], v[146:161]
	ds_read_b128 v[206:209], v182 offset:19456
	s_waitcnt lgkmcnt(9)
	v_mfma_f32_32x32x16_bf16 v[162:177], v[234:237], v[186:189], v[162:177]
	ds_read_b128 v[12:15], v16 offset:544
	ds_read_b128 v[210:213], v182 offset:544
	v_mfma_f32_32x32x16_bf16 v[146:161], v[238:241], v[186:189], v[146:161]
	ds_read_b128 v[214:217], v182 offset:19488
	s_waitcnt lgkmcnt(9)
	v_mfma_f32_32x32x16_bf16 v[162:177], v[242:245], v[190:193], v[162:177]
	v_mfma_f32_32x32x16_bf16 v[146:161], v[246:249], v[190:193], v[146:161]
	s_waitcnt lgkmcnt(6)
	v_mfma_f32_32x32x16_bf16 v[162:177], v[194:197], v[4:7], v[162:177]
	v_mfma_f32_32x32x16_bf16 v[146:161], v[198:201], v[4:7], v[146:161]
	s_waitcnt lgkmcnt(3)
	v_mfma_f32_32x32x16_bf16 v[162:177], v[202:205], v[8:11], v[162:177]
	v_mfma_f32_32x32x16_bf16 v[146:161], v[206:209], v[8:11], v[146:161]
	s_waitcnt lgkmcnt(0)
	v_mfma_f32_32x32x16_bf16 v[162:177], v[210:213], v[12:15], v[162:177]
	v_mfma_f32_32x32x16_bf16 v[146:161], v[214:217], v[12:15], v[146:161]
	ds_read_b64_tr_b16 v[190:191], v184 offset:0
	ds_read_b64_tr_b16 v[192:193], v184 offset:4736
	ds_read_b64_tr_b16 v[194:195], v184 offset:64
	ds_read_b64_tr_b16 v[196:197], v184 offset:4800
	ds_read_b64_tr_b16 v[198:199], v184 offset:128
	ds_read_b64_tr_b16 v[200:201], v184 offset:4864
	ds_read_b64_tr_b16 v[202:203], v184 offset:192
	ds_read_b64_tr_b16 v[204:205], v184 offset:4928
	ds_read_b64_tr_b16 v[206:207], v184 offset:256
	ds_read_b64_tr_b16 v[208:209], v184 offset:4992
	ds_read_b64_tr_b16 v[210:211], v184 offset:320
	ds_read_b64_tr_b16 v[212:213], v184 offset:5056
	ds_read_b64_tr_b16 v[214:215], v184 offset:384
	ds_read_b64_tr_b16 v[216:217], v184 offset:5120
	v_max3_f32 v2, v162, v146, v163
	v_max3_f32 v17, v147, v164, v148
	v_max3_f32 v2, v2, v165, v149
	v_max3_f32 v17, v17, v166, v150
	v_max3_f32 v2, v2, v167, v151
	v_max3_f32 v17, v17, v168, v152
	v_max3_f32 v2, v2, v169, v153
	v_max3_f32 v17, v17, v170, v154
	v_max3_f32 v2, v2, v171, v155
	v_max3_f32 v17, v17, v172, v156
	v_max3_f32 v2, v2, v173, v157
	v_max3_f32 v17, v17, v174, v158
	v_max3_f32 v2, v2, v175, v159
	v_max3_f32 v17, v17, v176, v160
	v_max3_f32 v2, v2, v17, v177
	v_max_f32_e32 v2, v2, v161
	v_mov_b32_e32 v218, v2
	v_add_f32_e32 v233, 0x41000000, v178
	v_mov_b32_e32 v254, 0
	v_permlane32_swap_b32_e32 v2, v218
	v_max_f32_e32 v2, v2, v218
	v_mul_f32_e32 v2, 0x3e16c740, v2
	v_cmp_gt_f32_e32 vcc, v2, v233
	s_cbranch_vccz .Ldc2_nr0
	v_max_f32_e32 v2, v178, v2
	v_sub_f32_e32 v219, v178, v2
	v_exp_f32_e32 v219, v219
	v_mov_b32_e32 v178, v2
	v_mov_b32_e32 v218, v2
	v_mul_f32_e32 v183, v183, v219
	v_mul_f32_e32 v130, v130, v219
	v_mul_f32_e32 v131, v131, v219
	v_mul_f32_e32 v132, v132, v219
	v_mul_f32_e32 v133, v133, v219
	v_mul_f32_e32 v134, v134, v219
	v_mul_f32_e32 v135, v135, v219
	v_mul_f32_e32 v136, v136, v219
	v_mul_f32_e32 v137, v137, v219
	v_mul_f32_e32 v138, v138, v219
	v_mul_f32_e32 v139, v139, v219
	v_mul_f32_e32 v140, v140, v219
	v_mul_f32_e32 v141, v141, v219
	v_mul_f32_e32 v142, v142, v219
	v_mul_f32_e32 v143, v143, v219
	v_mul_f32_e32 v144, v144, v219
	v_mul_f32_e32 v145, v145, v219
	v_mul_f32_e32 v114, v114, v219
	v_mul_f32_e32 v115, v115, v219
	v_mul_f32_e32 v116, v116, v219
	v_mul_f32_e32 v117, v117, v219
	v_mul_f32_e32 v118, v118, v219
	v_mul_f32_e32 v119, v119, v219
	v_mul_f32_e32 v120, v120, v219
	v_mul_f32_e32 v121, v121, v219
	v_mul_f32_e32 v122, v122, v219
	v_mul_f32_e32 v123, v123, v219
	v_mul_f32_e32 v124, v124, v219
	v_mul_f32_e32 v125, v125, v219
	v_mul_f32_e32 v126, v126, v219
	v_mul_f32_e32 v127, v127, v219
	v_mul_f32_e32 v128, v128, v219
	v_mul_f32_e32 v129, v129, v219
	v_mul_f32_e32 v98, v98, v219
	v_mul_f32_e32 v99, v99, v219
	v_mul_f32_e32 v100, v100, v219
	v_mul_f32_e32 v101, v101, v219
	v_mul_f32_e32 v102, v102, v219
	v_mul_f32_e32 v103, v103, v219
	v_mul_f32_e32 v104, v104, v219
	v_mul_f32_e32 v105, v105, v219
	v_mul_f32_e32 v106, v106, v219
	v_mul_f32_e32 v107, v107, v219
	v_mul_f32_e32 v108, v108, v219
	v_mul_f32_e32 v109, v109, v219
	v_mul_f32_e32 v110, v110, v219
	v_mul_f32_e32 v111, v111, v219
	v_mul_f32_e32 v112, v112, v219
	v_mul_f32_e32 v113, v113, v219
	v_mul_f32_e32 v82, v82, v219
	v_mul_f32_e32 v83, v83, v219
	v_mul_f32_e32 v84, v84, v219
	v_mul_f32_e32 v85, v85, v219
	v_mul_f32_e32 v86, v86, v219
	v_mul_f32_e32 v87, v87, v219
	v_mul_f32_e32 v88, v88, v219
	v_mul_f32_e32 v89, v89, v219
	v_mul_f32_e32 v90, v90, v219
	v_mul_f32_e32 v91, v91, v219
	v_mul_f32_e32 v92, v92, v219
	v_mul_f32_e32 v93, v93, v219
	v_mul_f32_e32 v94, v94, v219
	v_mul_f32_e32 v95, v95, v219
	v_mul_f32_e32 v96, v96, v219
	v_mul_f32_e32 v97, v97, v219
	v_mul_f32_e32 v66, v66, v219
	v_mul_f32_e32 v67, v67, v219
	v_mul_f32_e32 v68, v68, v219
	v_mul_f32_e32 v69, v69, v219
	v_mul_f32_e32 v70, v70, v219
	v_mul_f32_e32 v71, v71, v219
	v_mul_f32_e32 v72, v72, v219
	v_mul_f32_e32 v73, v73, v219
	v_mul_f32_e32 v74, v74, v219
	v_mul_f32_e32 v75, v75, v219
	v_mul_f32_e32 v76, v76, v219
	v_mul_f32_e32 v77, v77, v219
	v_mul_f32_e32 v78, v78, v219
	v_mul_f32_e32 v79, v79, v219
	v_mul_f32_e32 v80, v80, v219
	v_mul_f32_e32 v81, v81, v219
	v_mul_f32_e32 v50, v50, v219
	v_mul_f32_e32 v51, v51, v219
	v_mul_f32_e32 v52, v52, v219
	v_mul_f32_e32 v53, v53, v219
	v_mul_f32_e32 v54, v54, v219
	v_mul_f32_e32 v55, v55, v219
	v_mul_f32_e32 v56, v56, v219
	v_mul_f32_e32 v57, v57, v219
	v_mul_f32_e32 v58, v58, v219
	v_mul_f32_e32 v59, v59, v219
	v_mul_f32_e32 v60, v60, v219
	v_mul_f32_e32 v61, v61, v219
	v_mul_f32_e32 v62, v62, v219
	v_mul_f32_e32 v63, v63, v219
	v_mul_f32_e32 v64, v64, v219
	v_mul_f32_e32 v65, v65, v219
	v_mul_f32_e32 v34, v34, v219
	v_mul_f32_e32 v35, v35, v219
	v_mul_f32_e32 v36, v36, v219
	v_mul_f32_e32 v37, v37, v219
	v_mul_f32_e32 v38, v38, v219
	v_mul_f32_e32 v39, v39, v219
	v_mul_f32_e32 v40, v40, v219
	v_mul_f32_e32 v41, v41, v219
	v_mul_f32_e32 v42, v42, v219
	v_mul_f32_e32 v43, v43, v219
	v_mul_f32_e32 v44, v44, v219
	v_mul_f32_e32 v45, v45, v219
	v_mul_f32_e32 v46, v46, v219
	v_mul_f32_e32 v47, v47, v219
	v_mul_f32_e32 v48, v48, v219
	v_mul_f32_e32 v49, v49, v219
	v_mul_f32_e32 v18, v18, v219
	v_mul_f32_e32 v19, v19, v219
	v_mul_f32_e32 v20, v20, v219
	v_mul_f32_e32 v21, v21, v219
	v_mul_f32_e32 v22, v22, v219
	v_mul_f32_e32 v23, v23, v219
	v_mul_f32_e32 v24, v24, v219
	v_mul_f32_e32 v25, v25, v219
	v_mul_f32_e32 v26, v26, v219
	v_mul_f32_e32 v27, v27, v219
	v_mul_f32_e32 v28, v28, v219
	v_mul_f32_e32 v29, v29, v219
	v_mul_f32_e32 v30, v30, v219
	v_mul_f32_e32 v31, v31, v219
	v_mul_f32_e32 v32, v32, v219
	v_mul_f32_e32 v33, v33, v219
.Ldc2_nr0:
	v_fma_f32 v162, v162, s42, -v178
	v_fma_f32 v146, v146, s42, -v178
	v_fma_f32 v163, v163, s42, -v178
	v_exp_f32_e32 v162, v162
	v_fma_f32 v147, v147, s42, -v178
	v_exp_f32_e32 v146, v146
	v_fma_f32 v164, v164, s42, -v178
	v_exp_f32_e32 v163, v163
	v_fma_f32 v148, v148, s42, -v178
	v_exp_f32_e32 v147, v147
	v_fma_f32 v165, v165, s42, -v178
	v_add_f32_e32 v218, v162, v146
	v_exp_f32_e32 v164, v164
	v_fma_f32 v149, v149, s42, -v178
	v_exp_f32_e32 v148, v148
	v_cvt_pk_bf16_f32 v4, v162, v163
	v_fma_f32 v166, v166, s42, -v178
	v_add_f32_e32 v233, v163, v147
	v_exp_f32_e32 v165, v165
	v_add_f32_e32 v254, v254, v218
	v_cvt_pk_bf16_f32 v12, v146, v147
	v_fma_f32 v150, v150, s42, -v178
	v_exp_f32_e32 v149, v149
	v_fma_f32 v167, v167, s42, -v178
	v_add_f32_e32 v17, v164, v148
	v_exp_f32_e32 v166, v166
	v_add_f32_e32 v254, v254, v233
	v_fma_f32 v151, v151, s42, -v178
	v_exp_f32_e32 v150, v150
	v_cvt_pk_bf16_f32 v5, v164, v165
	v_fma_f32 v168, v168, s42, -v178
	v_add_f32_e32 v219, v165, v149
	v_exp_f32_e32 v167, v167
	v_add_f32_e32 v254, v254, v17
	v_cvt_pk_bf16_f32 v13, v148, v149
	v_fma_f32 v152, v152, s42, -v178
	v_exp_f32_e32 v151, v151
	v_fma_f32 v169, v169, s42, -v178
	v_add_f32_e32 v218, v166, v150
	v_exp_f32_e32 v168, v168
	v_add_f32_e32 v254, v254, v219
	v_fma_f32 v153, v153, s42, -v178
	v_exp_f32_e32 v152, v152
	v_cvt_pk_bf16_f32 v6, v166, v167
	v_fma_f32 v170, v170, s42, -v178
	v_add_f32_e32 v233, v167, v151
	v_exp_f32_e32 v169, v169
	v_add_f32_e32 v254, v254, v218
	v_cvt_pk_bf16_f32 v14, v150, v151
	v_fma_f32 v154, v154, s42, -v178
	v_exp_f32_e32 v153, v153
	v_fma_f32 v171, v171, s42, -v178
	v_add_f32_e32 v17, v168, v152
	v_exp_f32_e32 v170, v170
	v_add_f32_e32 v254, v254, v233
	v_fma_f32 v155, v155, s42, -v178
	v_exp_f32_e32 v154, v154
	v_cvt_pk_bf16_f32 v7, v168, v169
	v_fma_f32 v172, v172, s42, -v178
	v_add_f32_e32 v219, v169, v153
	v_exp_f32_e32 v171, v171
	v_add_f32_e32 v254, v254, v17
	v_cvt_pk_bf16_f32 v15, v152, v153
	v_fma_f32 v156, v156, s42, -v178
	v_exp_f32_e32 v155, v155
	v_fma_f32 v173, v173, s42, -v178
	v_add_f32_e32 v218, v170, v154
	v_exp_f32_e32 v172, v172
	v_add_f32_e32 v254, v254, v219
	v_fma_f32 v157, v157, s42, -v178
	v_exp_f32_e32 v156, v156
	v_cvt_pk_bf16_f32 v8, v170, v171
	v_fma_f32 v174, v174, s42, -v178
	v_add_f32_e32 v233, v171, v155
	v_exp_f32_e32 v173, v173
	v_add_f32_e32 v254, v254, v218
	v_cvt_pk_bf16_f32 v186, v154, v155
	v_fma_f32 v158, v158, s42, -v178
	v_exp_f32_e32 v157, v157
	v_fma_f32 v175, v175, s42, -v178
	v_add_f32_e32 v17, v172, v156
	v_exp_f32_e32 v174, v174
	v_add_f32_e32 v254, v254, v233
	v_fma_f32 v159, v159, s42, -v178
	v_exp_f32_e32 v158, v158
	v_cvt_pk_bf16_f32 v9, v172, v173
	v_fma_f32 v176, v176, s42, -v178
	v_add_f32_e32 v219, v173, v157
	v_exp_f32_e32 v175, v175
	v_add_f32_e32 v254, v254, v17
	v_cvt_pk_bf16_f32 v187, v156, v157
	v_fma_f32 v160, v160, s42, -v178
	v_exp_f32_e32 v159, v159
	v_fma_f32 v177, v177, s42, -v178
	v_add_f32_e32 v218, v174, v158
	v_exp_f32_e32 v176, v176
	v_add_f32_e32 v254, v254, v219
	v_fma_f32 v161, v161, s42, -v178
	v_exp_f32_e32 v160, v160
	v_cvt_pk_bf16_f32 v10, v174, v175
	v_add_f32_e32 v233, v175, v159
	v_exp_f32_e32 v177, v177
	v_add_f32_e32 v254, v254, v218
	v_cvt_pk_bf16_f32 v188, v158, v159
	v_exp_f32_e32 v161, v161
	v_add_f32_e32 v17, v176, v160
	v_add_f32_e32 v254, v254, v233
	v_cvt_pk_bf16_f32 v11, v176, v177
	v_add_f32_e32 v219, v177, v161
	v_add_f32_e32 v254, v254, v17
	v_cvt_pk_bf16_f32 v189, v160, v161
	v_add_f32_e32 v254, v254, v219
	v_add_f32_e32 v183, v183, v254
	s_waitcnt lgkmcnt(12)
	v_mfma_f32_32x32x16_bf16 v[130:145], v[190:193], v[4:7], v[130:145]
	ds_read_b64_tr_b16 v[234:235], v184 offset:448
	ds_read_b64_tr_b16 v[236:237], v184 offset:5184
	s_waitcnt lgkmcnt(12)
	v_mfma_f32_32x32x16_bf16 v[114:129], v[194:197], v[4:7], v[114:129]
	ds_read_b64_tr_b16 v[238:239], v184 offset:9472
	ds_read_b64_tr_b16 v[240:241], v184 offset:14208
	s_waitcnt lgkmcnt(12)
	v_mfma_f32_32x32x16_bf16 v[98:113], v[198:201], v[4:7], v[98:113]
	ds_read_b64_tr_b16 v[242:243], v184 offset:9536
	ds_read_b64_tr_b16 v[244:245], v184 offset:14272
	s_waitcnt lgkmcnt(12)
	v_mfma_f32_32x32x16_bf16 v[82:97], v[202:205], v[4:7], v[82:97]
	ds_read_b64_tr_b16 v[246:247], v184 offset:9600
	ds_read_b64_tr_b16 v[248:249], v184 offset:14336
	s_waitcnt lgkmcnt(12)
	v_mfma_f32_32x32x16_bf16 v[66:81], v[206:209], v[4:7], v[66:81]
	ds_read_b64_tr_b16 v[250:251], v184 offset:9664
	ds_read_b64_tr_b16 v[252:253], v184 offset:14400
	s_waitcnt lgkmcnt(12)
	v_mfma_f32_32x32x16_bf16 v[50:65], v[210:213], v[4:7], v[50:65]
	ds_read_b64_tr_b16 v[190:191], v184 offset:9728
	ds_read_b64_tr_b16 v[192:193], v184 offset:14464
	s_waitcnt lgkmcnt(12)
	v_mfma_f32_32x32x16_bf16 v[34:49], v[214:217], v[4:7], v[34:49]
	ds_read_b64_tr_b16 v[194:195], v184 offset:9792
	ds_read_b64_tr_b16 v[196:197], v184 offset:14528
	s_waitcnt lgkmcnt(12)
	v_mfma_f32_32x32x16_bf16 v[18:33], v[234:237], v[4:7], v[18:33]
	ds_read_b64_tr_b16 v[198:199], v184 offset:9856
	ds_read_b64_tr_b16 v[200:201], v184 offset:14592
	s_waitcnt lgkmcnt(12)
	v_mfma_f32_32x32x16_bf16 v[130:145], v[238:241], v[8:11], v[130:145]
	ds_read_b64_tr_b16 v[202:203], v184 offset:9920
	ds_read_b64_tr_b16 v[204:205], v184 offset:14656
	s_waitcnt lgkmcnt(12)
	v_mfma_f32_32x32x16_bf16 v[114:129], v[242:245], v[8:11], v[114:129]
	ds_read_b64_tr_b16 v[206:207], v184 offset:18944
	ds_read_b64_tr_b16 v[208:209], v184 offset:23680
	s_waitcnt lgkmcnt(12)
	v_mfma_f32_32x32x16_bf16 v[98:113], v[246:249], v[8:11], v[98:113]
	ds_read_b64_tr_b16 v[210:211], v184 offset:19008
	ds_read_b64_tr_b16 v[212:213], v184 offset:23744
	s_waitcnt lgkmcnt(12)
	v_mfma_f32_32x32x16_bf16 v[82:97], v[250:253], v[8:11], v[82:97]
	ds_read_b64_tr_b16 v[214:215], v184 offset:19072
	ds_read_b64_tr_b16 v[216:217], v184 offset:23808
	s_waitcnt lgkmcnt(12)
	v_mfma_f32_32x32x16_bf16 v[66:81], v[190:193], v[8:11], v[66:81]
	ds_read_b64_tr_b16 v[234:235], v184 offset:19136
	ds_read_b64_tr_b16 v[236:237], v184 offset:23872
	s_waitcnt lgkmcnt(12)
	v_mfma_f32_32x32x16_bf16 v[50:65], v[194:197], v[8:11], v[50:65]
	ds_read_b64_tr_b16 v[238:239], v184 offset:19200
	ds_read_b64_tr_b16 v[240:241], v184 offset:23936
	s_waitcnt lgkmcnt(12)
	v_mfma_f32_32x32x16_bf16 v[34:49], v[198:201], v[8:11], v[34:49]
	ds_read_b64_tr_b16 v[242:243], v184 offset:19264
	ds_read_b64_tr_b16 v[244:245], v184 offset:24000
	s_waitcnt lgkmcnt(12)
	v_mfma_f32_32x32x16_bf16 v[18:33], v[202:205], v[8:11], v[18:33]
	ds_read_b64_tr_b16 v[246:247], v184 offset:19328
	ds_read_b64_tr_b16 v[248:249], v184 offset:24064
	s_waitcnt lgkmcnt(12)
	v_mfma_f32_32x32x16_bf16 v[130:145], v[206:209], v[12:15], v[130:145]
	ds_read_b64_tr_b16 v[250:251], v184 offset:19392
	ds_read_b64_tr_b16 v[252:253], v184 offset:24128
	s_waitcnt lgkmcnt(12)
	v_mfma_f32_32x32x16_bf16 v[114:129], v[210:213], v[12:15], v[114:129]
	ds_read_b64_tr_b16 v[190:191], v184 offset:28416
	ds_read_b64_tr_b16 v[192:193], v184 offset:33152
	s_waitcnt lgkmcnt(12)
	v_mfma_f32_32x32x16_bf16 v[98:113], v[214:217], v[12:15], v[98:113]
	ds_read_b64_tr_b16 v[194:195], v184 offset:28480
	ds_read_b64_tr_b16 v[196:197], v184 offset:33216
	s_waitcnt lgkmcnt(12)
	v_mfma_f32_32x32x16_bf16 v[82:97], v[234:237], v[12:15], v[82:97]
	ds_read_b64_tr_b16 v[198:199], v184 offset:28544
	ds_read_b64_tr_b16 v[200:201], v184 offset:33280
	s_waitcnt lgkmcnt(12)
	v_mfma_f32_32x32x16_bf16 v[66:81], v[238:241], v[12:15], v[66:81]
	ds_read_b64_tr_b16 v[202:203], v184 offset:28608
	ds_read_b64_tr_b16 v[204:205], v184 offset:33344
	s_waitcnt lgkmcnt(12)
	v_mfma_f32_32x32x16_bf16 v[50:65], v[242:245], v[12:15], v[50:65]
	ds_read_b64_tr_b16 v[206:207], v184 offset:28672
	ds_read_b64_tr_b16 v[208:209], v184 offset:33408
	s_waitcnt lgkmcnt(12)
	v_mfma_f32_32x32x16_bf16 v[34:49], v[246:249], v[12:15], v[34:49]
	ds_read_b64_tr_b16 v[210:211], v184 offset:28736
	ds_read_b64_tr_b16 v[212:213], v184 offset:33472
	s_waitcnt lgkmcnt(12)
	v_mfma_f32_32x32x16_bf16 v[18:33], v[250:253], v[12:15], v[18:33]
	ds_read_b64_tr_b16 v[214:215], v184 offset:28800
	ds_read_b64_tr_b16 v[216:217], v184 offset:33536
	s_waitcnt lgkmcnt(12)
	v_mfma_f32_32x32x16_bf16 v[130:145], v[190:193], v[186:189], v[130:145]
	ds_read_b64_tr_b16 v[234:235], v184 offset:28864
	ds_read_b64_tr_b16 v[236:237], v184 offset:33600
	s_waitcnt lgkmcnt(12)
	v_mfma_f32_32x32x16_bf16 v[114:129], v[194:197], v[186:189], v[114:129]
	s_waitcnt lgkmcnt(10)
	v_mfma_f32_32x32x16_bf16 v[98:113], v[198:201], v[186:189], v[98:113]
	s_waitcnt lgkmcnt(8)
	v_mfma_f32_32x32x16_bf16 v[82:97], v[202:205], v[186:189], v[82:97]
	s_waitcnt lgkmcnt(6)
	v_mfma_f32_32x32x16_bf16 v[66:81], v[206:209], v[186:189], v[66:81]
	s_waitcnt lgkmcnt(4)
	v_mfma_f32_32x32x16_bf16 v[50:65], v[210:213], v[186:189], v[50:65]
	s_waitcnt lgkmcnt(2)
	v_mfma_f32_32x32x16_bf16 v[34:49], v[214:217], v[186:189], v[34:49]
	s_waitcnt lgkmcnt(0)
	v_mfma_f32_32x32x16_bf16 v[18:33], v[234:237], v[186:189], v[18:33]
	s_waitcnt lgkmcnt(0)
	s_barrier
	ds_read_b128 v[4:7], v16 offset:0
	ds_read_b128 v[194:197], v182 offset:37888
	ds_read_b128 v[198:201], v182 offset:56832
	ds_read_b128 v[8:11], v16 offset:32
	ds_read_b128 v[202:205], v182 offset:37920
	ds_read_b128 v[206:209], v182 offset:56864
	ds_read_b128 v[12:15], v16 offset:64
	ds_read_b128 v[210:213], v182 offset:37952
	ds_read_b128 v[214:217], v182 offset:56896
	s_waitcnt lgkmcnt(6)
	v_mfma_f32_32x32x16_bf16 v[162:177], v[194:197], v[4:7], 0
	ds_read_b128 v[186:189], v16 offset:96
	ds_read_b128 v[234:237], v182 offset:37984
	ds_read_b128 v[238:241], v182 offset:56928
	ds_read_b128 v[190:193], v16 offset:128
	ds_read_b128 v[242:245], v182 offset:38016
	v_mfma_f32_32x32x16_bf16 v[146:161], v[198:201], v[4:7], 0
	ds_read_b128 v[246:249], v182 offset:56960
	s_waitcnt lgkmcnt(9)
	v_mfma_f32_32x32x16_bf16 v[162:177], v[202:205], v[8:11], v[162:177]
	ds_read_b128 v[4:7], v16 offset:160
	ds_read_b128 v[194:197], v182 offset:38048
	v_mfma_f32_32x32x16_bf16 v[146:161], v[206:209], v[8:11], v[146:161]
	ds_read_b128 v[198:201], v182 offset:56992
	s_waitcnt lgkmcnt(9)
	v_mfma_f32_32x32x16_bf16 v[162:177], v[210:213], v[12:15], v[162:177]
	ds_read_b128 v[8:11], v16 offset:192
	ds_read_b128 v[202:205], v182 offset:38080
	v_mfma_f32_32x32x16_bf16 v[146:161], v[214:217], v[12:15], v[146:161]
	ds_read_b128 v[206:209], v182 offset:57024
	s_waitcnt lgkmcnt(9)
	v_mfma_f32_32x32x16_bf16 v[162:177], v[234:237], v[186:189], v[162:177]
	ds_read_b128 v[12:15], v16 offset:224
	ds_read_b128 v[210:213], v182 offset:38112
	v_mfma_f32_32x32x16_bf16 v[146:161], v[238:241], v[186:189], v[146:161]
	ds_read_b128 v[214:217], v182 offset:57056
	s_waitcnt lgkmcnt(9)
	v_mfma_f32_32x32x16_bf16 v[162:177], v[242:245], v[190:193], v[162:177]
	ds_read_b128 v[186:189], v16 offset:256
	ds_read_b128 v[234:237], v182 offset:38144
	v_mfma_f32_32x32x16_bf16 v[146:161], v[246:249], v[190:193], v[146:161]
	ds_read_b128 v[238:241], v182 offset:57088
	s_waitcnt lgkmcnt(9)
	v_mfma_f32_32x32x16_bf16 v[162:177], v[194:197], v[4:7], v[162:177]
	ds_read_b128 v[190:193], v16 offset:288
	ds_read_b128 v[242:245], v182 offset:38176
	v_mfma_f32_32x32x16_bf16 v[146:161], v[198:201], v[4:7], v[146:161]
	ds_read_b128 v[246:249], v182 offset:57120
	s_waitcnt lgkmcnt(9)
	v_mfma_f32_32x32x16_bf16 v[162:177], v[202:205], v[8:11], v[162:177]
	ds_read_b128 v[4:7], v16 offset:320
	ds_read_b128 v[194:197], v182 offset:38208
	v_mfma_f32_32x32x16_bf16 v[146:161], v[206:209], v[8:11], v[146:161]
	ds_read_b128 v[198:201], v182 offset:57152
	s_waitcnt lgkmcnt(9)
	v_mfma_f32_32x32x16_bf16 v[162:177], v[210:213], v[12:15], v[162:177]
	ds_read_b128 v[8:11], v16 offset:352
	ds_read_b128 v[202:205], v182 offset:38240
	v_mfma_f32_32x32x16_bf16 v[146:161], v[214:217], v[12:15], v[146:161]
	ds_read_b128 v[206:209], v182 offset:57184
	s_waitcnt lgkmcnt(9)
	v_mfma_f32_32x32x16_bf16 v[162:177], v[234:237], v[186:189], v[162:177]
	ds_read_b128 v[12:15], v16 offset:384
	ds_read_b128 v[210:213], v182 offset:38272
	v_mfma_f32_32x32x16_bf16 v[146:161], v[238:241], v[186:189], v[146:161]
	ds_read_b128 v[214:217], v182 offset:57216
	s_waitcnt lgkmcnt(9)
	v_mfma_f32_32x32x16_bf16 v[162:177], v[242:245], v[190:193], v[162:177]
	ds_read_b128 v[186:189], v16 offset:416
	ds_read_b128 v[234:237], v182 offset:38304
	v_mfma_f32_32x32x16_bf16 v[146:161], v[246:249], v[190:193], v[146:161]
	ds_read_b128 v[238:241], v182 offset:57248
	s_waitcnt lgkmcnt(9)
	v_mfma_f32_32x32x16_bf16 v[162:177], v[194:197], v[4:7], v[162:177]
	ds_read_b128 v[190:193], v16 offset:448
	ds_read_b128 v[242:245], v182 offset:38336
	v_mfma_f32_32x32x16_bf16 v[146:161], v[198:201], v[4:7], v[146:161]
	ds_read_b128 v[246:249], v182 offset:57280
	s_waitcnt lgkmcnt(9)
	v_mfma_f32_32x32x16_bf16 v[162:177], v[202:205], v[8:11], v[162:177]
	ds_read_b128 v[4:7], v16 offset:480
	ds_read_b128 v[194:197], v182 offset:38368
	v_mfma_f32_32x32x16_bf16 v[146:161], v[206:209], v[8:11], v[146:161]
	ds_read_b128 v[198:201], v182 offset:57312
	s_waitcnt lgkmcnt(9)
	v_mfma_f32_32x32x16_bf16 v[162:177], v[210:213], v[12:15], v[162:177]
	ds_read_b128 v[8:11], v16 offset:512
	ds_read_b128 v[202:205], v182 offset:38400
	v_mfma_f32_32x32x16_bf16 v[146:161], v[214:217], v[12:15], v[146:161]
	ds_read_b128 v[206:209], v182 offset:57344
	s_waitcnt lgkmcnt(9)
	v_mfma_f32_32x32x16_bf16 v[162:177], v[234:237], v[186:189], v[162:177]
	ds_read_b128 v[12:15], v16 offset:544
	ds_read_b128 v[210:213], v182 offset:38432
	v_mfma_f32_32x32x16_bf16 v[146:161], v[238:241], v[186:189], v[146:161]
	ds_read_b128 v[214:217], v182 offset:57376
	s_waitcnt lgkmcnt(9)
	v_mfma_f32_32x32x16_bf16 v[162:177], v[242:245], v[190:193], v[162:177]
	v_mfma_f32_32x32x16_bf16 v[146:161], v[246:249], v[190:193], v[146:161]
	s_waitcnt lgkmcnt(6)
	v_mfma_f32_32x32x16_bf16 v[162:177], v[194:197], v[4:7], v[162:177]
	v_mfma_f32_32x32x16_bf16 v[146:161], v[198:201], v[4:7], v[146:161]
	s_waitcnt lgkmcnt(3)
	v_mfma_f32_32x32x16_bf16 v[162:177], v[202:205], v[8:11], v[162:177]
	v_mfma_f32_32x32x16_bf16 v[146:161], v[206:209], v[8:11], v[146:161]
	s_waitcnt lgkmcnt(0)
	v_mfma_f32_32x32x16_bf16 v[162:177], v[210:213], v[12:15], v[162:177]
	v_mfma_f32_32x32x16_bf16 v[146:161], v[214:217], v[12:15], v[146:161]
	ds_read_b64_tr_b16 v[190:191], v185 offset:0
	ds_read_b64_tr_b16 v[192:193], v185 offset:4736
	ds_read_b64_tr_b16 v[194:195], v185 offset:64
	ds_read_b64_tr_b16 v[196:197], v185 offset:4800
	ds_read_b64_tr_b16 v[198:199], v185 offset:128
	ds_read_b64_tr_b16 v[200:201], v185 offset:4864
	ds_read_b64_tr_b16 v[202:203], v185 offset:192
	ds_read_b64_tr_b16 v[204:205], v185 offset:4928
	ds_read_b64_tr_b16 v[206:207], v185 offset:256
	ds_read_b64_tr_b16 v[208:209], v185 offset:4992
	ds_read_b64_tr_b16 v[210:211], v185 offset:320
	ds_read_b64_tr_b16 v[212:213], v185 offset:5056
	ds_read_b64_tr_b16 v[214:215], v185 offset:384
	ds_read_b64_tr_b16 v[216:217], v185 offset:5120
	v_max3_f32 v2, v162, v146, v163
	v_max3_f32 v17, v147, v164, v148
	v_max3_f32 v2, v2, v165, v149
	v_max3_f32 v17, v17, v166, v150
	v_max3_f32 v2, v2, v167, v151
	v_max3_f32 v17, v17, v168, v152
	v_max3_f32 v2, v2, v169, v153
	v_max3_f32 v17, v17, v170, v154
	v_max3_f32 v2, v2, v171, v155
	v_max3_f32 v17, v17, v172, v156
	v_max3_f32 v2, v2, v173, v157
	v_max3_f32 v17, v17, v174, v158
	v_max3_f32 v2, v2, v175, v159
	v_max3_f32 v17, v17, v176, v160
	v_max3_f32 v2, v2, v17, v177
	v_max_f32_e32 v2, v2, v161
	v_mov_b32_e32 v218, v2
	v_add_f32_e32 v233, 0x41000000, v178
	v_mov_b32_e32 v254, 0
	v_permlane32_swap_b32_e32 v2, v218
	v_max_f32_e32 v2, v2, v218
	v_mul_f32_e32 v2, 0x3e16c740, v2
	v_cmp_gt_f32_e32 vcc, v2, v233
	s_cbranch_vccz .Ldc2_nr1
	v_max_f32_e32 v2, v178, v2
	v_sub_f32_e32 v219, v178, v2
	v_exp_f32_e32 v219, v219
	v_mov_b32_e32 v178, v2
	v_mov_b32_e32 v218, v2
	v_mul_f32_e32 v183, v183, v219
	v_mul_f32_e32 v130, v130, v219
	v_mul_f32_e32 v131, v131, v219
	v_mul_f32_e32 v132, v132, v219
	v_mul_f32_e32 v133, v133, v219
	v_mul_f32_e32 v134, v134, v219
	v_mul_f32_e32 v135, v135, v219
	v_mul_f32_e32 v136, v136, v219
	v_mul_f32_e32 v137, v137, v219
	v_mul_f32_e32 v138, v138, v219
	v_mul_f32_e32 v139, v139, v219
	v_mul_f32_e32 v140, v140, v219
	v_mul_f32_e32 v141, v141, v219
	v_mul_f32_e32 v142, v142, v219
	v_mul_f32_e32 v143, v143, v219
	v_mul_f32_e32 v144, v144, v219
	v_mul_f32_e32 v145, v145, v219
	v_mul_f32_e32 v114, v114, v219
	v_mul_f32_e32 v115, v115, v219
	v_mul_f32_e32 v116, v116, v219
	v_mul_f32_e32 v117, v117, v219
	v_mul_f32_e32 v118, v118, v219
	v_mul_f32_e32 v119, v119, v219
	v_mul_f32_e32 v120, v120, v219
	v_mul_f32_e32 v121, v121, v219
	v_mul_f32_e32 v122, v122, v219
	v_mul_f32_e32 v123, v123, v219
	v_mul_f32_e32 v124, v124, v219
	v_mul_f32_e32 v125, v125, v219
	v_mul_f32_e32 v126, v126, v219
	v_mul_f32_e32 v127, v127, v219
	v_mul_f32_e32 v128, v128, v219
	v_mul_f32_e32 v129, v129, v219
	v_mul_f32_e32 v98, v98, v219
	v_mul_f32_e32 v99, v99, v219
	v_mul_f32_e32 v100, v100, v219
	v_mul_f32_e32 v101, v101, v219
	v_mul_f32_e32 v102, v102, v219
	v_mul_f32_e32 v103, v103, v219
	v_mul_f32_e32 v104, v104, v219
	v_mul_f32_e32 v105, v105, v219
	v_mul_f32_e32 v106, v106, v219
	v_mul_f32_e32 v107, v107, v219
	v_mul_f32_e32 v108, v108, v219
	v_mul_f32_e32 v109, v109, v219
	v_mul_f32_e32 v110, v110, v219
	v_mul_f32_e32 v111, v111, v219
	v_mul_f32_e32 v112, v112, v219
	v_mul_f32_e32 v113, v113, v219
	v_mul_f32_e32 v82, v82, v219
	v_mul_f32_e32 v83, v83, v219
	v_mul_f32_e32 v84, v84, v219
	v_mul_f32_e32 v85, v85, v219
	v_mul_f32_e32 v86, v86, v219
	v_mul_f32_e32 v87, v87, v219
	v_mul_f32_e32 v88, v88, v219
	v_mul_f32_e32 v89, v89, v219
	v_mul_f32_e32 v90, v90, v219
	v_mul_f32_e32 v91, v91, v219
	v_mul_f32_e32 v92, v92, v219
	v_mul_f32_e32 v93, v93, v219
	v_mul_f32_e32 v94, v94, v219
	v_mul_f32_e32 v95, v95, v219
	v_mul_f32_e32 v96, v96, v219
	v_mul_f32_e32 v97, v97, v219
	v_mul_f32_e32 v66, v66, v219
	v_mul_f32_e32 v67, v67, v219
	v_mul_f32_e32 v68, v68, v219
	v_mul_f32_e32 v69, v69, v219
	v_mul_f32_e32 v70, v70, v219
	v_mul_f32_e32 v71, v71, v219
	v_mul_f32_e32 v72, v72, v219
	v_mul_f32_e32 v73, v73, v219
	v_mul_f32_e32 v74, v74, v219
	v_mul_f32_e32 v75, v75, v219
	v_mul_f32_e32 v76, v76, v219
	v_mul_f32_e32 v77, v77, v219
	v_mul_f32_e32 v78, v78, v219
	v_mul_f32_e32 v79, v79, v219
	v_mul_f32_e32 v80, v80, v219
	v_mul_f32_e32 v81, v81, v219
	v_mul_f32_e32 v50, v50, v219
	v_mul_f32_e32 v51, v51, v219
	v_mul_f32_e32 v52, v52, v219
	v_mul_f32_e32 v53, v53, v219
	v_mul_f32_e32 v54, v54, v219
	v_mul_f32_e32 v55, v55, v219
	v_mul_f32_e32 v56, v56, v219
	v_mul_f32_e32 v57, v57, v219
	v_mul_f32_e32 v58, v58, v219
	v_mul_f32_e32 v59, v59, v219
	v_mul_f32_e32 v60, v60, v219
	v_mul_f32_e32 v61, v61, v219
	v_mul_f32_e32 v62, v62, v219
	v_mul_f32_e32 v63, v63, v219
	v_mul_f32_e32 v64, v64, v219
	v_mul_f32_e32 v65, v65, v219
	v_mul_f32_e32 v34, v34, v219
	v_mul_f32_e32 v35, v35, v219
	v_mul_f32_e32 v36, v36, v219
	v_mul_f32_e32 v37, v37, v219
	v_mul_f32_e32 v38, v38, v219
	v_mul_f32_e32 v39, v39, v219
	v_mul_f32_e32 v40, v40, v219
	v_mul_f32_e32 v41, v41, v219
	v_mul_f32_e32 v42, v42, v219
	v_mul_f32_e32 v43, v43, v219
	v_mul_f32_e32 v44, v44, v219
	v_mul_f32_e32 v45, v45, v219
	v_mul_f32_e32 v46, v46, v219
	v_mul_f32_e32 v47, v47, v219
	v_mul_f32_e32 v48, v48, v219
	v_mul_f32_e32 v49, v49, v219
	v_mul_f32_e32 v18, v18, v219
	v_mul_f32_e32 v19, v19, v219
	v_mul_f32_e32 v20, v20, v219
	v_mul_f32_e32 v21, v21, v219
	v_mul_f32_e32 v22, v22, v219
	v_mul_f32_e32 v23, v23, v219
	v_mul_f32_e32 v24, v24, v219
	v_mul_f32_e32 v25, v25, v219
	v_mul_f32_e32 v26, v26, v219
	v_mul_f32_e32 v27, v27, v219
	v_mul_f32_e32 v28, v28, v219
	v_mul_f32_e32 v29, v29, v219
	v_mul_f32_e32 v30, v30, v219
	v_mul_f32_e32 v31, v31, v219
	v_mul_f32_e32 v32, v32, v219
	v_mul_f32_e32 v33, v33, v219
